# residual epilogues: three line-touch loads ahead of the first 8-load group prefetch the residual lines of groups 2-4
# baseline (speedup 1.0000x reference)
.LBB0_411:
	v_lshl_or_b32 v168, s76, 8, v198
	v_add_u32_e32 v156, 0x800, v168
	v_ashrrev_i32_e32 v157, 31, v156
	v_lshlrev_b64 v[160:161], 2, v[156:157]
	s_ashr_i32 s49, s46, 3
	v_lshl_add_u64 v[164:165], s[18:19], 0, v[160:161]
	v_lshl_add_u64 v[156:157], s[12:13], 0, v[160:161]
	v_mad_i64_i32 v[160:161], s[38:39], s49, v211, v[164:165]
	global_load_dwordx4 v[156:159], v[156:157], off
	s_add_i32 s50, s49, 8
	s_add_i32 s48, s49, 16
	s_add_i32 s47, s49, 24
	s_add_i32 s81, s49, 32
	s_add_i32 s80, s49, 40
	s_add_i32 s79, s49, 48
	s_add_i32 s78, s49, 56
	s_lshl_b32 s77, s46, 8
	global_load_dwordx4 v[160:163], v[160:161], off
	v_mad_i64_i32 v[212:213], s[38:39], s50, v211, v[164:165]
	global_load_dwordx4 v[212:215], v[212:213], off
	v_mad_i64_i32 v[216:217], s[38:39], s48, v211, v[164:165]
	global_load_dwordx4 v[216:219], v[216:217], off
	v_mad_i64_i32 v[220:221], s[38:39], s47, v211, v[164:165]
	global_load_dwordx4 v[220:223], v[220:221], off
	v_mad_i64_i32 v[230:231], s[38:39], s81, v211, v[164:165]
	global_load_dwordx4 v[230:233], v[230:231], off
	v_mad_i64_i32 v[234:235], s[38:39], s80, v211, v[164:165]
	global_load_dwordx4 v[234:237], v[234:235], off
	v_mad_i64_i32 v[238:239], s[38:39], s79, v211, v[164:165]
	global_load_dwordx4 v[238:241], v[238:239], off
	v_mad_i64_i32 v[246:247], s[38:39], s78, v211, v[164:165]
	global_load_dwordx4 v[246:249], v[246:247], off
	v_ashrrev_i32_e32 v169, 31, v168
	v_readfirstlane_b32 s82, v180
	s_waitcnt vmcnt(7)
	v_pk_add_f32 v[160:161], v[156:157], v[160:161]
	v_pk_add_f32 v[162:163], v[158:159], v[162:163]
	s_waitcnt vmcnt(6)
	v_pk_add_f32 v[160:161], v[160:161], v[212:213]
	v_pk_add_f32 v[162:163], v[162:163], v[214:215]
	s_waitcnt vmcnt(5)
	v_pk_add_f32 v[160:161], v[160:161], v[216:217]
	v_pk_add_f32 v[162:163], v[162:163], v[218:219]
	s_waitcnt vmcnt(4)
	v_pk_add_f32 v[160:161], v[160:161], v[220:221]
	v_pk_add_f32 v[162:163], v[162:163], v[222:223]
	s_waitcnt vmcnt(3)
	v_pk_add_f32 v[160:161], v[160:161], v[230:231]
	v_pk_add_f32 v[162:163], v[162:163], v[232:233]
	s_waitcnt vmcnt(2)
	v_pk_add_f32 v[160:161], v[160:161], v[234:235]
	v_pk_add_f32 v[162:163], v[162:163], v[236:237]
	s_waitcnt vmcnt(1)
	v_pk_add_f32 v[160:161], v[160:161], v[238:239]
	v_pk_add_f32 v[162:163], v[162:163], v[240:241]
	s_waitcnt vmcnt(0)
	v_pk_add_f32 v[158:159], v[162:163], v[248:249]
	v_pk_add_f32 v[160:161], v[160:161], v[246:247]
	v_pk_mul_f32 v[156:157], v[158:159], 0.5 op_sel_hi:[1, 0]
	v_pk_mul_f32 v[158:159], v[160:161], 0.5 op_sel_hi:[1, 0]
	v_add_u32_e32 v160, 0x810, v168
	v_ashrrev_i32_e32 v161, 31, v160
	v_lshlrev_b64 v[164:165], 2, v[160:161]
	v_lshl_add_u64 v[170:171], s[18:19], 0, v[164:165]
	v_lshl_add_u64 v[160:161], s[12:13], 0, v[164:165]
	v_mad_i64_i32 v[164:165], s[38:39], s49, v211, v[170:171]
	global_load_dwordx4 v[160:163], v[160:161], off
	global_load_dwordx4 v[164:167], v[164:165], off
	v_mad_i64_i32 v[212:213], s[38:39], s50, v211, v[170:171]
	global_load_dwordx4 v[212:215], v[212:213], off
	v_mad_i64_i32 v[216:217], s[38:39], s48, v211, v[170:171]
	global_load_dwordx4 v[216:219], v[216:217], off
	v_mad_i64_i32 v[220:221], s[38:39], s47, v211, v[170:171]
	global_load_dwordx4 v[220:223], v[220:221], off
	v_mad_i64_i32 v[230:231], s[38:39], s81, v211, v[170:171]
	global_load_dwordx4 v[230:233], v[230:231], off
	v_mad_i64_i32 v[234:235], s[38:39], s80, v211, v[170:171]
	global_load_dwordx4 v[234:237], v[234:235], off
	v_mad_i64_i32 v[238:239], s[38:39], s79, v211, v[170:171]
	global_load_dwordx4 v[238:241], v[238:239], off
	v_mad_i64_i32 v[246:247], s[38:39], s78, v211, v[170:171]
	global_load_dwordx4 v[246:249], v[246:247], off
	s_waitcnt vmcnt(7)
	v_pk_add_f32 v[164:165], v[160:161], v[164:165]
	v_pk_add_f32 v[166:167], v[162:163], v[166:167]
	s_waitcnt vmcnt(6)
	v_pk_add_f32 v[164:165], v[164:165], v[212:213]
	v_pk_add_f32 v[166:167], v[166:167], v[214:215]
	s_waitcnt vmcnt(5)
	v_pk_add_f32 v[164:165], v[164:165], v[216:217]
	v_pk_add_f32 v[166:167], v[166:167], v[218:219]
	s_waitcnt vmcnt(4)
	v_pk_add_f32 v[164:165], v[164:165], v[220:221]
	v_pk_add_f32 v[166:167], v[166:167], v[222:223]
	s_waitcnt vmcnt(3)
	v_pk_add_f32 v[164:165], v[164:165], v[230:231]
	v_pk_add_f32 v[166:167], v[166:167], v[232:233]
	s_waitcnt vmcnt(2)
	v_pk_add_f32 v[164:165], v[164:165], v[234:235]
	v_pk_add_f32 v[166:167], v[166:167], v[236:237]
	s_waitcnt vmcnt(1)
	v_pk_add_f32 v[164:165], v[164:165], v[238:239]
	v_pk_add_f32 v[166:167], v[166:167], v[240:241]
	s_waitcnt vmcnt(0)
	v_pk_add_f32 v[162:163], v[166:167], v[248:249]
	v_pk_add_f32 v[164:165], v[164:165], v[246:247]
	v_pk_mul_f32 v[160:161], v[162:163], 0.5 op_sel_hi:[1, 0]
	v_pk_mul_f32 v[162:163], v[164:165], 0.5 op_sel_hi:[1, 0]
	v_add_u32_e32 v164, 0x880, v168
	v_ashrrev_i32_e32 v165, 31, v164
	v_lshlrev_b64 v[170:171], 2, v[164:165]
	v_lshl_add_u64 v[174:175], s[18:19], 0, v[170:171]
	v_lshl_add_u64 v[164:165], s[12:13], 0, v[170:171]
	v_mad_i64_i32 v[170:171], s[38:39], s49, v211, v[174:175]
	global_load_dwordx4 v[164:167], v[164:165], off
	global_load_dwordx4 v[170:173], v[170:171], off
	v_mad_i64_i32 v[212:213], s[38:39], s50, v211, v[174:175]
	global_load_dwordx4 v[212:215], v[212:213], off
	v_mad_i64_i32 v[216:217], s[38:39], s48, v211, v[174:175]
	global_load_dwordx4 v[216:219], v[216:217], off
	v_mad_i64_i32 v[220:221], s[38:39], s47, v211, v[174:175]
	global_load_dwordx4 v[220:223], v[220:221], off
	v_mad_i64_i32 v[230:231], s[38:39], s81, v211, v[174:175]
	global_load_dwordx4 v[230:233], v[230:231], off
	v_mad_i64_i32 v[234:235], s[38:39], s80, v211, v[174:175]
	global_load_dwordx4 v[234:237], v[234:235], off
	v_mad_i64_i32 v[238:239], s[38:39], s79, v211, v[174:175]
	global_load_dwordx4 v[238:241], v[238:239], off
	v_mad_i64_i32 v[246:247], s[38:39], s78, v211, v[174:175]
	global_load_dwordx4 v[246:249], v[246:247], off
	s_waitcnt vmcnt(7)
	v_pk_add_f32 v[170:171], v[164:165], v[170:171]
	v_pk_add_f32 v[172:173], v[166:167], v[172:173]
	s_waitcnt vmcnt(6)
	v_pk_add_f32 v[170:171], v[170:171], v[212:213]
	v_pk_add_f32 v[172:173], v[172:173], v[214:215]
	s_waitcnt vmcnt(5)
	v_pk_add_f32 v[170:171], v[170:171], v[216:217]
	v_pk_add_f32 v[172:173], v[172:173], v[218:219]
	s_waitcnt vmcnt(4)
	v_pk_add_f32 v[170:171], v[170:171], v[220:221]
	v_pk_add_f32 v[172:173], v[172:173], v[222:223]
	s_waitcnt vmcnt(3)
	v_pk_add_f32 v[170:171], v[170:171], v[230:231]
	v_pk_add_f32 v[172:173], v[172:173], v[232:233]
	s_waitcnt vmcnt(2)
	v_pk_add_f32 v[170:171], v[170:171], v[234:235]
	v_pk_add_f32 v[172:173], v[172:173], v[236:237]
	s_waitcnt vmcnt(1)
	v_pk_add_f32 v[170:171], v[170:171], v[238:239]
	v_pk_add_f32 v[172:173], v[172:173], v[240:241]
	s_waitcnt vmcnt(0)
	v_pk_add_f32 v[166:167], v[172:173], v[248:249]
	v_pk_add_f32 v[170:171], v[170:171], v[246:247]
	v_pk_mul_f32 v[164:165], v[166:167], 0.5 op_sel_hi:[1, 0]
	v_pk_mul_f32 v[166:167], v[170:171], 0.5 op_sel_hi:[1, 0]
	v_add_u32_e32 v170, 0x890, v168
	v_ashrrev_i32_e32 v171, 31, v170
	v_lshlrev_b64 v[174:175], 2, v[170:171]
	v_lshl_add_u64 v[178:179], s[18:19], 0, v[174:175]
	v_lshl_add_u64 v[170:171], s[12:13], 0, v[174:175]
	v_mad_i64_i32 v[174:175], s[38:39], s49, v211, v[178:179]
	global_load_dwordx4 v[170:173], v[170:171], off
	global_load_dwordx4 v[174:177], v[174:175], off
	v_mad_i64_i32 v[212:213], s[38:39], s50, v211, v[178:179]
	global_load_dwordx4 v[212:215], v[212:213], off
	v_mad_i64_i32 v[216:217], s[38:39], s48, v211, v[178:179]
	global_load_dwordx4 v[216:219], v[216:217], off
	v_mad_i64_i32 v[220:221], s[38:39], s47, v211, v[178:179]
	global_load_dwordx4 v[220:223], v[220:221], off
	v_mad_i64_i32 v[230:231], s[38:39], s81, v211, v[178:179]
	global_load_dwordx4 v[230:233], v[230:231], off
	v_mad_i64_i32 v[234:235], s[38:39], s80, v211, v[178:179]
	global_load_dwordx4 v[234:237], v[234:235], off
	v_mad_i64_i32 v[238:239], s[38:39], s79, v211, v[178:179]
	global_load_dwordx4 v[238:241], v[238:239], off
	v_mad_i64_i32 v[246:247], s[38:39], s78, v211, v[178:179]
	global_load_dwordx4 v[246:249], v[246:247], off
	v_lshlrev_b64 v[168:169], 2, v[168:169]
	s_waitcnt vmcnt(7)
	v_pk_add_f32 v[174:175], v[170:171], v[174:175]
	v_pk_add_f32 v[176:177], v[172:173], v[176:177]
	s_waitcnt vmcnt(6)
	v_pk_add_f32 v[174:175], v[174:175], v[212:213]
	v_pk_add_f32 v[176:177], v[176:177], v[214:215]
	s_waitcnt vmcnt(5)
	v_pk_add_f32 v[174:175], v[174:175], v[216:217]
	v_pk_add_f32 v[176:177], v[176:177], v[218:219]
	s_waitcnt vmcnt(4)
	v_pk_add_f32 v[174:175], v[174:175], v[220:221]
	v_pk_add_f32 v[176:177], v[176:177], v[222:223]
	s_waitcnt vmcnt(3)
	v_pk_add_f32 v[174:175], v[174:175], v[230:231]
	v_pk_add_f32 v[176:177], v[176:177], v[232:233]
	s_waitcnt vmcnt(2)
	v_pk_add_f32 v[174:175], v[174:175], v[234:235]
	v_pk_add_f32 v[176:177], v[176:177], v[236:237]
	s_waitcnt vmcnt(1)
	v_pk_add_f32 v[174:175], v[174:175], v[238:239]
	v_pk_add_f32 v[176:177], v[176:177], v[240:241]
	v_add_u32_e32 v178, s77, v181
	v_ashrrev_i32_e32 v179, 31, v178
	v_or_b32_e32 v228, 16, v178
	v_ashrrev_i32_e32 v229, 31, v228
	v_lshlrev_b64 v[244:245], 12, v[228:229]
	s_waitcnt vmcnt(0)
	v_pk_add_f32 v[172:173], v[176:177], v[248:249]
	v_pk_add_f32 v[174:175], v[174:175], v[246:247]
	v_pk_mul_f32 v[170:171], v[172:173], 0.5 op_sel_hi:[1, 0]
	v_pk_mul_f32 v[172:173], v[174:175], 0.5 op_sel_hi:[1, 0]
	v_lshl_add_u64 v[174:175], s[2:3], 0, v[168:169]
	v_lshlrev_b64 v[176:177], 12, v[178:179]
	v_lshl_add_u64 v[224:225], v[174:175], 0, v[176:177]
	v_mbcnt_lo_u32_b32 v180, -1, 0
	v_mbcnt_hi_u32_b32 v180, -1, v180
	v_lshrrev_b32_e32 v180, 4, v180
	v_and_b32_e32 v181, 1, v180
	v_lshlrev_b32_e32 v181, 16, v181
	v_lshrrev_b32_e32 v184, 1, v180
	v_lshl_add_u32 v181, v184, 9, v181
	v_lshlrev_b32_e32 v180, 4, v180
	v_sub_u32_e32 v180, v181, v180
	v_mov_b32_e32 v181, 0
	v_lshl_add_u64 v[180:181], v[224:225], 0, v[180:181]
	v_mov_b32_e32 v186, 0x20000
	v_mov_b32_e32 v187, 0
	v_lshl_add_u64 v[184:185], v[180:181], 0, v[186:187]
	global_load_dword v182, v[184:185], off
	v_mov_b32_e32 v186, 0x60000
	v_lshl_add_u64 v[184:185], v[184:185], 0, v[186:187]
	global_load_dword v182, v[184:185], off
	v_mov_b32_e32 v186, 0x20000
	v_lshl_add_u64 v[184:185], v[184:185], 0, v[186:187]
	global_load_dword v182, v[184:185], off
	global_load_dwordx4 v[212:215], v[224:225], off
	global_load_dwordx4 v[216:219], v[224:225], off offset:64
	global_load_dwordx4 v[220:223], v[224:225], off offset:512
	s_nop 0
	global_load_dwordx4 v[224:227], v[224:225], off offset:576
	v_lshl_add_u64 v[240:241], v[174:175], 0, v[244:245]
	global_load_dwordx4 v[228:231], v[240:241], off
	global_load_dwordx4 v[232:235], v[240:241], off offset:64
	global_load_dwordx4 v[236:239], v[240:241], off offset:512
	s_nop 0
	global_load_dwordx4 v[240:243], v[240:241], off offset:576
	s_waitcnt vmcnt(7)
	v_pk_fma_f32 v[124:125], v[124:125], v[158:159], v[212:213]
	v_lshl_add_u64 v[212:213], s[16:17], 0, v[176:177]
	v_lshl_add_u64 v[212:213], v[212:213], 0, v[168:169]
	s_waitcnt vmcnt(5)
	v_pk_fma_f32 v[114:115], v[114:115], v[164:165], v[222:223]
	v_pk_fma_f32 v[112:113], v[112:113], v[166:167], v[220:221]
	global_store_dwordx4 v[212:213], v[112:115], off offset:512
	s_waitcnt vmcnt(5)
	v_pk_fma_f32 v[106:107], v[106:107], v[170:171], v[226:227]
	v_pk_fma_f32 v[104:105], v[104:105], v[172:173], v[224:225]
	v_lshl_add_u64 v[112:113], s[16:17], 0, v[244:245]
	v_lshl_add_u64 v[112:113], v[112:113], 0, v[168:169]
	s_waitcnt vmcnt(1)
	v_pk_fma_f32 v[98:99], v[98:99], v[170:171], v[242:243]
	v_pk_fma_f32 v[96:97], v[96:97], v[172:173], v[240:241]
	global_store_dwordx4 v[212:213], v[104:107], off offset:576
	global_store_dwordx4 v[112:113], v[96:99], off offset:576
	v_pk_fma_f32 v[126:127], v[126:127], v[156:157], v[214:215]
	v_pk_fma_f32 v[106:107], v[118:119], v[156:157], v[230:231]
	v_pk_fma_f32 v[104:105], v[116:117], v[158:159], v[228:229]
	v_or_b32_e32 v96, 32, v178
	v_pk_fma_f32 v[122:123], v[122:123], v[160:161], v[218:219]
	v_pk_fma_f32 v[120:121], v[120:121], v[162:163], v[216:217]
	global_store_dwordx4 v[112:113], v[104:107], off
	v_pk_fma_f32 v[102:103], v[102:103], v[164:165], v[238:239]
	v_pk_fma_f32 v[100:101], v[100:101], v[166:167], v[236:237]
	v_pk_fma_f32 v[106:107], v[110:111], v[160:161], v[234:235]
	v_pk_fma_f32 v[104:105], v[108:109], v[162:163], v[232:233]
	v_ashrrev_i32_e32 v97, 31, v96
	global_store_dwordx4 v[212:213], v[124:127], off
	global_store_dwordx4 v[212:213], v[120:123], off offset:64
	global_store_dwordx4 v[112:113], v[104:107], off offset:64
	global_store_dwordx4 v[112:113], v[100:103], off offset:512
	v_lshlrev_b64 v[212:213], 12, v[96:97]
	v_or_b32_e32 v112, 48, v178
	v_lshl_add_u64 v[108:109], v[174:175], 0, v[212:213]
	v_ashrrev_i32_e32 v113, 31, v112
	global_load_dwordx4 v[96:99], v[108:109], off
	global_load_dwordx4 v[100:103], v[108:109], off offset:64
	global_load_dwordx4 v[104:107], v[108:109], off offset:512
	s_nop 0
	global_load_dwordx4 v[108:111], v[108:109], off offset:576
	v_lshlrev_b64 v[178:179], 12, v[112:113]
	v_lshl_add_u64 v[124:125], v[174:175], 0, v[178:179]
	global_load_dwordx4 v[112:115], v[124:125], off
	global_load_dwordx4 v[116:119], v[124:125], off offset:64
	global_load_dwordx4 v[120:123], v[124:125], off offset:512
	s_nop 0
	global_load_dwordx4 v[124:127], v[124:125], off offset:576
	s_waitcnt vmcnt(7)
	v_pk_fma_f32 v[92:93], v[92:93], v[158:159], v[96:97]
	v_lshl_add_u64 v[96:97], s[16:17], 0, v[212:213]
	v_lshl_add_u64 v[96:97], v[96:97], 0, v[168:169]
	s_waitcnt vmcnt(5)
	v_pk_fma_f32 v[82:83], v[82:83], v[164:165], v[106:107]
	v_pk_fma_f32 v[80:81], v[80:81], v[166:167], v[104:105]
	global_store_dwordx4 v[96:97], v[80:83], off offset:512
	s_waitcnt vmcnt(5)
	v_pk_fma_f32 v[74:75], v[74:75], v[170:171], v[110:111]
	v_pk_fma_f32 v[72:73], v[72:73], v[172:173], v[108:109]
	v_lshl_add_u64 v[80:81], s[16:17], 0, v[178:179]
	v_pk_fma_f32 v[94:95], v[94:95], v[156:157], v[98:99]
	v_pk_fma_f32 v[90:91], v[90:91], v[160:161], v[102:103]
	v_pk_fma_f32 v[88:89], v[88:89], v[162:163], v[100:101]
	global_store_dwordx4 v[96:97], v[72:75], off offset:576
	v_lshl_add_u64 v[80:81], v[80:81], 0, v[168:169]
	global_store_dwordx4 v[96:97], v[92:95], off
	s_waitcnt vmcnt(6)
	v_pk_fma_f32 v[74:75], v[86:87], v[156:157], v[114:115]
	v_pk_fma_f32 v[72:73], v[84:85], v[158:159], v[112:113]
	global_store_dwordx4 v[96:97], v[88:91], off offset:64
	global_store_dwordx4 v[80:81], v[72:75], off
	s_waitcnt vmcnt(6)
	v_pk_fma_f32 v[70:71], v[70:71], v[164:165], v[122:123]
	v_pk_fma_f32 v[68:69], v[68:69], v[166:167], v[120:121]
	v_pk_fma_f32 v[74:75], v[78:79], v[160:161], v[118:119]
	v_pk_fma_f32 v[72:73], v[76:77], v[162:163], v[116:117]
	s_waitcnt vmcnt(5)
	v_pk_fma_f32 v[66:67], v[66:67], v[170:171], v[126:127]
	v_pk_fma_f32 v[64:65], v[64:65], v[172:173], v[124:125]
	v_lshl_add_u64 v[96:97], v[176:177], 0, s[22:23]
	global_store_dwordx4 v[80:81], v[72:75], off offset:64
	global_store_dwordx4 v[80:81], v[68:71], off offset:512
	global_store_dwordx4 v[80:81], v[64:67], off offset:576
	v_lshl_add_u64 v[76:77], v[174:175], 0, v[96:97]
	global_load_dwordx4 v[64:67], v[76:77], off
	global_load_dwordx4 v[68:71], v[76:77], off offset:64
	global_load_dwordx4 v[72:75], v[76:77], off offset:512
	s_nop 0
	global_load_dwordx4 v[76:79], v[76:77], off offset:576
	v_lshl_add_u64 v[98:99], v[176:177], 0, s[24:25]
	v_lshl_add_u64 v[92:93], v[174:175], 0, v[98:99]
	global_load_dwordx4 v[80:83], v[92:93], off
	global_load_dwordx4 v[84:87], v[92:93], off offset:64
	global_load_dwordx4 v[88:91], v[92:93], off offset:512
	s_nop 0
	global_load_dwordx4 v[92:95], v[92:93], off offset:576
	s_waitcnt vmcnt(7)
	v_pk_fma_f32 v[60:61], v[60:61], v[158:159], v[64:65]
	v_lshl_add_u64 v[64:65], s[16:17], 0, v[96:97]
	v_lshl_add_u64 v[64:65], v[64:65], 0, v[168:169]
	s_waitcnt vmcnt(5)
	v_pk_fma_f32 v[50:51], v[50:51], v[164:165], v[74:75]
	v_pk_fma_f32 v[48:49], v[48:49], v[166:167], v[72:73]
	global_store_dwordx4 v[64:65], v[48:51], off offset:512
	s_waitcnt vmcnt(5)
	v_pk_fma_f32 v[42:43], v[42:43], v[170:171], v[78:79]
	v_pk_fma_f32 v[40:41], v[40:41], v[172:173], v[76:77]
	v_lshl_add_u64 v[48:49], s[16:17], 0, v[98:99]
	v_pk_fma_f32 v[62:63], v[62:63], v[156:157], v[66:67]
	v_pk_fma_f32 v[58:59], v[58:59], v[160:161], v[70:71]
	v_pk_fma_f32 v[56:57], v[56:57], v[162:163], v[68:69]
	global_store_dwordx4 v[64:65], v[40:43], off offset:576
	v_lshl_add_u64 v[48:49], v[48:49], 0, v[168:169]
	global_store_dwordx4 v[64:65], v[60:63], off
	s_waitcnt vmcnt(6)
	v_pk_fma_f32 v[42:43], v[54:55], v[156:157], v[82:83]
	v_pk_fma_f32 v[40:41], v[52:53], v[158:159], v[80:81]
	global_store_dwordx4 v[64:65], v[56:59], off offset:64
	global_store_dwordx4 v[48:49], v[40:43], off
	s_waitcnt vmcnt(6)
	v_pk_fma_f32 v[38:39], v[38:39], v[164:165], v[90:91]
	v_pk_fma_f32 v[36:37], v[36:37], v[166:167], v[88:89]
	v_pk_fma_f32 v[42:43], v[46:47], v[160:161], v[86:87]
	v_pk_fma_f32 v[40:41], v[44:45], v[162:163], v[84:85]
	s_waitcnt vmcnt(5)
	v_pk_fma_f32 v[30:31], v[30:31], v[170:171], v[94:95]
	v_pk_fma_f32 v[28:29], v[28:29], v[172:173], v[92:93]
	v_lshl_add_u64 v[64:65], v[176:177], 0, s[26:27]
	global_store_dwordx4 v[48:49], v[40:43], off offset:64
	global_store_dwordx4 v[48:49], v[36:39], off offset:512
	global_store_dwordx4 v[48:49], v[28:31], off offset:576
	v_lshl_add_u64 v[44:45], v[174:175], 0, v[64:65]
	global_load_dwordx4 v[28:31], v[44:45], off
	global_load_dwordx4 v[36:39], v[44:45], off offset:64
	global_load_dwordx4 v[40:43], v[44:45], off offset:512
	s_nop 0
	global_load_dwordx4 v[44:47], v[44:45], off offset:576
	v_lshl_add_u64 v[66:67], v[176:177], 0, s[28:29]
	v_lshl_add_u64 v[60:61], v[174:175], 0, v[66:67]
	global_load_dwordx4 v[48:51], v[60:61], off
	global_load_dwordx4 v[52:55], v[60:61], off offset:64
	global_load_dwordx4 v[56:59], v[60:61], off offset:512
	s_nop 0
	global_load_dwordx4 v[60:63], v[60:61], off offset:576
	s_waitcnt vmcnt(7)
	v_pk_fma_f32 v[28:29], v[32:33], v[158:159], v[28:29]
	v_lshl_add_u64 v[32:33], s[16:17], 0, v[64:65]
	v_lshl_add_u64 v[32:33], v[32:33], 0, v[168:169]
	s_waitcnt vmcnt(5)
	v_pk_fma_f32 v[18:19], v[18:19], v[164:165], v[42:43]
	v_pk_fma_f32 v[16:17], v[16:17], v[166:167], v[40:41]
	global_store_dwordx4 v[32:33], v[16:19], off offset:512
	s_waitcnt vmcnt(5)
	v_pk_fma_f32 v[10:11], v[10:11], v[170:171], v[46:47]
	v_pk_fma_f32 v[8:9], v[8:9], v[172:173], v[44:45]
	v_lshl_add_u64 v[16:17], s[16:17], 0, v[66:67]
	global_store_dwordx4 v[32:33], v[8:11], off offset:576
	v_lshl_add_u64 v[16:17], v[16:17], 0, v[168:169]
	v_pk_fma_f32 v[30:31], v[34:35], v[156:157], v[30:31]
	s_waitcnt vmcnt(5)
	v_pk_fma_f32 v[10:11], v[22:23], v[156:157], v[50:51]
	v_pk_fma_f32 v[8:9], v[20:21], v[158:159], v[48:49]
	v_pk_fma_f32 v[26:27], v[26:27], v[160:161], v[38:39]
	v_pk_fma_f32 v[24:25], v[24:25], v[162:163], v[36:37]
	global_store_dwordx4 v[16:17], v[8:11], off
	s_waitcnt vmcnt(4)
	v_pk_fma_f32 v[6:7], v[6:7], v[164:165], v[58:59]
	v_pk_fma_f32 v[4:5], v[4:5], v[166:167], v[56:57]
	v_pk_fma_f32 v[10:11], v[14:15], v[160:161], v[54:55]
	v_pk_fma_f32 v[8:9], v[12:13], v[162:163], v[52:53]
	s_waitcnt vmcnt(3)
	v_pk_fma_f32 v[2:3], v[2:3], v[170:171], v[62:63]
	v_pk_fma_f32 v[0:1], v[0:1], v[172:173], v[60:61]
	global_store_dwordx4 v[32:33], v[28:31], off
	global_store_dwordx4 v[32:33], v[24:27], off offset:64
	global_store_dwordx4 v[16:17], v[8:11], off offset:64
	global_store_dwordx4 v[16:17], v[4:7], off offset:512
	global_store_dwordx4 v[16:17], v[0:3], off offset:576
	s_waitcnt vmcnt(0)
	s_barrier
	s_and_saveexec_b64 s[38:39], s[4:5]
	s_cbranch_execz .LBB0_425
	s_lshl_b32 s40, s46, 2
	s_ashr_i32 s41, s40, 31
	s_lshl_b64 s[40:41], s[40:41], 2
	s_add_u32 s40, s65, s40
	s_addc_u32 s41, s66, s41
	s_getreg_b32 s42, hwreg(HW_REG_XCC_ID, 0, 4)
	global_load_dwordx4 v[0:3], v129, s[40:41]
	s_and_b32 s40, s42, 15
	s_add_i32 s40, s40, 1
	s_waitcnt vmcnt(0)
	v_cmp_ne_u32_e32 vcc, s40, v2
	s_nop 1
	v_cndmask_b32_e64 v2, 0, 1, vcc
	v_cmp_ne_u32_e32 vcc, s40, v3
	v_lshlrev_b32_e32 v2, 2, v2
	s_nop 0
	v_cndmask_b32_e64 v3, 0, 1, vcc
	v_cmp_ne_u32_e32 vcc, s40, v1
	v_lshlrev_b32_e32 v3, 3, v3
	v_or_b32_e32 v2, v3, v2
	v_cndmask_b32_e64 v1, 0, 1, vcc
	v_cmp_ne_u32_e32 vcc, s40, v0
	v_lshlrev_b32_e32 v1, 1, v1
	s_nop 0
	v_cndmask_b32_e64 v0, 0, 1, vcc
	v_or_b32_e32 v0, v0, v1
	v_and_b32_e32 v0, 3, v0
	v_or_b32_e32 v0, v0, v2
	v_and_b32_e32 v0, 15, v0
	v_cmp_eq_u32_e32 vcc, 0, v0
	s_cbranch_vccnz .LBB0_414
	buffer_wbl2 sc1
	s_waitcnt vmcnt(0)

.LBB0_1174:
	v_lshl_or_b32 v172, s42, 8, v198
	v_add_u32_e32 v156, 0x1400, v172
	v_ashrrev_i32_e32 v157, 31, v156
	v_lshlrev_b64 v[160:161], 2, v[156:157]
	s_ashr_i32 s54, s44, 3
	v_lshl_add_u64 v[164:165], s[2:3], 0, v[160:161]
	v_lshl_add_u64 v[156:157], s[12:13], 0, v[160:161]
	v_mad_i64_i32 v[160:161], s[46:47], s54, v211, v[164:165]
	global_load_dwordx4 v[156:159], v[156:157], off
	s_add_i32 s55, s54, 8
	s_add_i32 s53, s54, 16
	s_add_i32 s52, s54, 24
	s_add_i32 s81, s54, 32
	s_add_i32 s80, s54, 40
	s_add_i32 s43, s54, 48
	s_add_i32 s37, s54, 56
	s_lshl_b32 s35, s44, 8
	global_load_dwordx4 v[160:163], v[160:161], off
	v_mad_i64_i32 v[212:213], s[46:47], s55, v211, v[164:165]
	global_load_dwordx4 v[212:215], v[212:213], off
	v_mad_i64_i32 v[216:217], s[46:47], s53, v211, v[164:165]
	global_load_dwordx4 v[216:219], v[216:217], off
	v_mad_i64_i32 v[220:221], s[46:47], s52, v211, v[164:165]
	global_load_dwordx4 v[220:223], v[220:221], off
	v_mad_i64_i32 v[224:225], s[46:47], s81, v211, v[164:165]
	global_load_dwordx4 v[224:227], v[224:225], off
	v_mad_i64_i32 v[228:229], s[46:47], s80, v211, v[164:165]
	global_load_dwordx4 v[228:231], v[228:229], off
	v_mad_i64_i32 v[232:233], s[46:47], s43, v211, v[164:165]
	global_load_dwordx4 v[232:235], v[232:233], off
	v_mad_i64_i32 v[236:237], s[46:47], s37, v211, v[164:165]
	global_load_dwordx4 v[236:239], v[236:237], off
	v_ashrrev_i32_e32 v173, 31, v172
	v_readfirstlane_b32 s82, v180
	s_waitcnt vmcnt(7)
	v_pk_add_f32 v[160:161], v[156:157], v[160:161]
	v_pk_add_f32 v[162:163], v[158:159], v[162:163]
	s_waitcnt vmcnt(6)
	v_pk_add_f32 v[160:161], v[160:161], v[212:213]
	v_pk_add_f32 v[162:163], v[162:163], v[214:215]
	s_waitcnt vmcnt(5)
	v_pk_add_f32 v[160:161], v[160:161], v[216:217]
	v_pk_add_f32 v[162:163], v[162:163], v[218:219]
	s_waitcnt vmcnt(4)
	v_pk_add_f32 v[160:161], v[160:161], v[220:221]
	v_pk_add_f32 v[162:163], v[162:163], v[222:223]
	s_waitcnt vmcnt(3)
	v_pk_add_f32 v[160:161], v[160:161], v[224:225]
	v_pk_add_f32 v[162:163], v[162:163], v[226:227]
	s_waitcnt vmcnt(2)
	v_pk_add_f32 v[160:161], v[160:161], v[228:229]
	v_pk_add_f32 v[162:163], v[162:163], v[230:231]
	s_waitcnt vmcnt(1)
	v_pk_add_f32 v[166:167], v[160:161], v[232:233]
	v_pk_add_f32 v[162:163], v[162:163], v[234:235]
	s_waitcnt vmcnt(0)
	v_pk_add_f32 v[156:157], v[162:163], v[238:239]
	v_add_u32_e32 v160, 0x1410, v172
	v_ashrrev_i32_e32 v161, 31, v160
	v_lshlrev_b64 v[164:165], 2, v[160:161]
	v_lshl_add_u64 v[168:169], s[2:3], 0, v[164:165]
	v_lshl_add_u64 v[160:161], s[12:13], 0, v[164:165]
	v_mad_i64_i32 v[164:165], s[46:47], s54, v211, v[168:169]
	v_pk_add_f32 v[158:159], v[166:167], v[236:237]
	global_load_dwordx4 v[160:163], v[160:161], off
	global_load_dwordx4 v[164:167], v[164:165], off
	v_mad_i64_i32 v[212:213], s[46:47], s55, v211, v[168:169]
	global_load_dwordx4 v[212:215], v[212:213], off
	v_mad_i64_i32 v[216:217], s[46:47], s53, v211, v[168:169]
	global_load_dwordx4 v[216:219], v[216:217], off
	v_mad_i64_i32 v[220:221], s[46:47], s52, v211, v[168:169]
	global_load_dwordx4 v[220:223], v[220:221], off
	v_mad_i64_i32 v[224:225], s[46:47], s81, v211, v[168:169]
	global_load_dwordx4 v[224:227], v[224:225], off
	v_mad_i64_i32 v[228:229], s[46:47], s80, v211, v[168:169]
	global_load_dwordx4 v[228:231], v[228:229], off
	v_mad_i64_i32 v[232:233], s[46:47], s43, v211, v[168:169]
	global_load_dwordx4 v[232:235], v[232:233], off
	v_mad_i64_i32 v[236:237], s[46:47], s37, v211, v[168:169]
	global_load_dwordx4 v[236:239], v[236:237], off
	s_waitcnt vmcnt(7)
	v_pk_add_f32 v[164:165], v[160:161], v[164:165]
	v_pk_add_f32 v[166:167], v[162:163], v[166:167]
	s_waitcnt vmcnt(6)
	v_pk_add_f32 v[164:165], v[164:165], v[212:213]
	v_pk_add_f32 v[166:167], v[166:167], v[214:215]
	s_waitcnt vmcnt(5)
	v_pk_add_f32 v[164:165], v[164:165], v[216:217]
	v_pk_add_f32 v[166:167], v[166:167], v[218:219]
	s_waitcnt vmcnt(4)
	v_pk_add_f32 v[164:165], v[164:165], v[220:221]
	v_pk_add_f32 v[166:167], v[166:167], v[222:223]
	s_waitcnt vmcnt(3)
	v_pk_add_f32 v[164:165], v[164:165], v[224:225]
	v_pk_add_f32 v[166:167], v[166:167], v[226:227]
	s_waitcnt vmcnt(2)
	v_pk_add_f32 v[164:165], v[164:165], v[228:229]
	v_pk_add_f32 v[166:167], v[166:167], v[230:231]
	s_waitcnt vmcnt(1)
	v_pk_add_f32 v[170:171], v[164:165], v[232:233]
	v_pk_add_f32 v[166:167], v[166:167], v[234:235]
	s_waitcnt vmcnt(0)
	v_pk_add_f32 v[160:161], v[166:167], v[238:239]
	v_add_u32_e32 v164, 0x1480, v172
	v_ashrrev_i32_e32 v165, 31, v164
	v_lshlrev_b64 v[168:169], 2, v[164:165]
	v_lshl_add_u64 v[174:175], s[2:3], 0, v[168:169]
	v_lshl_add_u64 v[164:165], s[12:13], 0, v[168:169]
	v_mad_i64_i32 v[168:169], s[46:47], s54, v211, v[174:175]
	v_pk_add_f32 v[162:163], v[170:171], v[236:237]
	global_load_dwordx4 v[164:167], v[164:165], off
	global_load_dwordx4 v[168:171], v[168:169], off
	v_mad_i64_i32 v[212:213], s[46:47], s55, v211, v[174:175]
	global_load_dwordx4 v[212:215], v[212:213], off
	v_mad_i64_i32 v[216:217], s[46:47], s53, v211, v[174:175]
	global_load_dwordx4 v[216:219], v[216:217], off
	v_mad_i64_i32 v[220:221], s[46:47], s52, v211, v[174:175]
	global_load_dwordx4 v[220:223], v[220:221], off
	v_mad_i64_i32 v[224:225], s[46:47], s81, v211, v[174:175]
	global_load_dwordx4 v[224:227], v[224:225], off
	v_mad_i64_i32 v[228:229], s[46:47], s80, v211, v[174:175]
	global_load_dwordx4 v[228:231], v[228:229], off
	v_mad_i64_i32 v[232:233], s[46:47], s43, v211, v[174:175]
	global_load_dwordx4 v[232:235], v[232:233], off
	v_mad_i64_i32 v[236:237], s[46:47], s37, v211, v[174:175]
	global_load_dwordx4 v[236:239], v[236:237], off
	s_waitcnt vmcnt(7)
	v_pk_add_f32 v[168:169], v[164:165], v[168:169]
	v_pk_add_f32 v[170:171], v[166:167], v[170:171]
	s_waitcnt vmcnt(6)
	v_pk_add_f32 v[168:169], v[168:169], v[212:213]
	v_pk_add_f32 v[170:171], v[170:171], v[214:215]
	s_waitcnt vmcnt(5)
	v_pk_add_f32 v[168:169], v[168:169], v[216:217]
	v_pk_add_f32 v[170:171], v[170:171], v[218:219]
	s_waitcnt vmcnt(4)
	v_pk_add_f32 v[168:169], v[168:169], v[220:221]
	v_pk_add_f32 v[170:171], v[170:171], v[222:223]
	s_waitcnt vmcnt(3)
	v_pk_add_f32 v[168:169], v[168:169], v[224:225]
	v_pk_add_f32 v[170:171], v[170:171], v[226:227]
	s_waitcnt vmcnt(2)
	v_pk_add_f32 v[168:169], v[168:169], v[228:229]
	v_pk_add_f32 v[170:171], v[170:171], v[230:231]
	s_waitcnt vmcnt(1)
	v_pk_add_f32 v[176:177], v[168:169], v[232:233]
	v_pk_add_f32 v[170:171], v[170:171], v[234:235]
	s_waitcnt vmcnt(0)
	v_pk_add_f32 v[164:165], v[170:171], v[238:239]
	v_add_u32_e32 v168, 0x1490, v172
	v_ashrrev_i32_e32 v169, 31, v168
	v_lshlrev_b64 v[174:175], 2, v[168:169]
	v_lshl_add_u64 v[178:179], s[2:3], 0, v[174:175]
	v_lshl_add_u64 v[168:169], s[12:13], 0, v[174:175]
	v_mad_i64_i32 v[174:175], s[46:47], s54, v211, v[178:179]
	v_pk_add_f32 v[166:167], v[176:177], v[236:237]
	global_load_dwordx4 v[168:171], v[168:169], off
	global_load_dwordx4 v[174:177], v[174:175], off
	v_mad_i64_i32 v[212:213], s[46:47], s55, v211, v[178:179]
	global_load_dwordx4 v[212:215], v[212:213], off
	v_mad_i64_i32 v[216:217], s[46:47], s53, v211, v[178:179]
	global_load_dwordx4 v[216:219], v[216:217], off
	v_mad_i64_i32 v[220:221], s[46:47], s52, v211, v[178:179]
	global_load_dwordx4 v[220:223], v[220:221], off
	v_mad_i64_i32 v[224:225], s[46:47], s81, v211, v[178:179]
	global_load_dwordx4 v[224:227], v[224:225], off
	v_mad_i64_i32 v[228:229], s[46:47], s80, v211, v[178:179]
	global_load_dwordx4 v[228:231], v[228:229], off
	v_mad_i64_i32 v[232:233], s[46:47], s43, v211, v[178:179]
	global_load_dwordx4 v[232:235], v[232:233], off
	v_mad_i64_i32 v[236:237], s[46:47], s37, v211, v[178:179]
	global_load_dwordx4 v[236:239], v[236:237], off
	v_lshlrev_b64 v[172:173], 2, v[172:173]
	s_waitcnt vmcnt(7)
	v_pk_add_f32 v[174:175], v[168:169], v[174:175]
	v_pk_add_f32 v[176:177], v[170:171], v[176:177]
	s_waitcnt vmcnt(6)
	v_pk_add_f32 v[174:175], v[174:175], v[212:213]
	v_pk_add_f32 v[176:177], v[176:177], v[214:215]
	s_waitcnt vmcnt(5)
	v_pk_add_f32 v[174:175], v[174:175], v[216:217]
	v_pk_add_f32 v[176:177], v[176:177], v[218:219]
	s_waitcnt vmcnt(4)
	v_pk_add_f32 v[174:175], v[174:175], v[220:221]
	v_pk_add_f32 v[176:177], v[176:177], v[222:223]
	s_waitcnt vmcnt(3)
	v_pk_add_f32 v[174:175], v[174:175], v[224:225]
	v_pk_add_f32 v[176:177], v[176:177], v[226:227]
	s_waitcnt vmcnt(2)
	v_pk_add_f32 v[174:175], v[174:175], v[228:229]
	v_pk_add_f32 v[176:177], v[176:177], v[230:231]
	s_waitcnt vmcnt(1)
	v_pk_add_f32 v[204:205], v[174:175], v[232:233]
	v_pk_add_f32 v[170:171], v[176:177], v[234:235]
	v_add_u32_e32 v178, s35, v181
	v_ashrrev_i32_e32 v179, 31, v178
	s_waitcnt vmcnt(0)
	v_pk_add_f32 v[168:169], v[170:171], v[238:239]
	v_pk_add_f32 v[170:171], v[204:205], v[236:237]
	v_lshl_add_u64 v[174:175], s[0:1], 0, v[172:173]
	v_lshlrev_b64 v[176:177], 12, v[178:179]
	v_lshl_add_u64 v[204:205], v[174:175], 0, v[176:177]
	v_mbcnt_lo_u32_b32 v180, -1, 0
	v_mbcnt_hi_u32_b32 v180, -1, v180
	v_lshrrev_b32_e32 v180, 4, v180
	v_and_b32_e32 v181, 1, v180
	v_lshlrev_b32_e32 v181, 16, v181
	v_lshrrev_b32_e32 v184, 1, v180
	v_lshl_add_u32 v181, v184, 9, v181
	v_lshlrev_b32_e32 v180, 4, v180
	v_sub_u32_e32 v180, v181, v180
	v_mov_b32_e32 v181, 0
	v_lshl_add_u64 v[180:181], v[204:205], 0, v[180:181]
	v_mov_b32_e32 v186, 0x20000
	v_mov_b32_e32 v187, 0
	v_lshl_add_u64 v[184:185], v[180:181], 0, v[186:187]
	global_load_dword v182, v[184:185], off
	v_mov_b32_e32 v186, 0x60000
	v_lshl_add_u64 v[184:185], v[184:185], 0, v[186:187]
	global_load_dword v182, v[184:185], off
	v_mov_b32_e32 v186, 0x20000
	v_lshl_add_u64 v[184:185], v[184:185], 0, v[186:187]
	global_load_dword v182, v[184:185], off
	global_load_dwordx4 v[212:215], v[204:205], off
	global_load_dwordx4 v[216:219], v[204:205], off offset:64
	global_load_dwordx4 v[220:223], v[204:205], off offset:512
	global_load_dwordx4 v[224:227], v[204:205], off offset:576
	v_or_b32_e32 v204, 16, v178
	v_ashrrev_i32_e32 v205, 31, v204
	v_lshlrev_b64 v[204:205], 12, v[204:205]
	v_lshl_add_u64 v[206:207], v[174:175], 0, v[204:205]
	global_load_dwordx4 v[228:231], v[206:207], off
	global_load_dwordx4 v[232:235], v[206:207], off offset:64
	global_load_dwordx4 v[236:239], v[206:207], off offset:512
	global_load_dwordx4 v[240:243], v[206:207], off offset:576
	v_lshl_add_u64 v[206:207], s[0:1], 0, v[176:177]
	v_lshl_add_u64 v[206:207], v[206:207], 0, v[172:173]
	s_waitcnt vmcnt(7)
	v_pk_fma_f32 v[126:127], v[126:127], v[156:157], v[214:215]
	v_pk_fma_f32 v[124:125], v[124:125], v[158:159], v[212:213]
	s_waitcnt vmcnt(5)
	v_pk_fma_f32 v[110:111], v[110:111], v[164:165], v[222:223]
	v_pk_fma_f32 v[108:109], v[108:109], v[166:167], v[220:221]
	global_store_dwordx4 v[206:207], v[108:111], off offset:512
	s_waitcnt vmcnt(5)
	v_pk_fma_f32 v[106:107], v[106:107], v[168:169], v[226:227]
	v_pk_fma_f32 v[104:105], v[104:105], v[170:171], v[224:225]
	v_lshl_add_u64 v[108:109], s[0:1], 0, v[204:205]
	v_lshl_add_u64 v[108:109], v[108:109], 0, v[172:173]
	s_waitcnt vmcnt(1)
	v_pk_fma_f32 v[98:99], v[98:99], v[168:169], v[242:243]
	v_pk_fma_f32 v[96:97], v[96:97], v[170:171], v[240:241]
	global_store_dwordx4 v[108:109], v[96:99], off offset:576
	global_store_dwordx4 v[206:207], v[104:107], off offset:576
	v_pk_fma_f32 v[122:123], v[122:123], v[160:161], v[218:219]
	v_or_b32_e32 v96, 32, v178
	v_pk_fma_f32 v[106:107], v[118:119], v[156:157], v[230:231]
	v_pk_fma_f32 v[104:105], v[116:117], v[158:159], v[228:229]
	v_ashrrev_i32_e32 v97, 31, v96
	v_pk_fma_f32 v[120:121], v[120:121], v[162:163], v[216:217]
	global_store_dwordx4 v[108:109], v[104:107], off
	v_pk_fma_f32 v[102:103], v[102:103], v[164:165], v[238:239]
	v_pk_fma_f32 v[100:101], v[100:101], v[166:167], v[236:237]
	v_pk_fma_f32 v[106:107], v[114:115], v[160:161], v[234:235]
	v_pk_fma_f32 v[104:105], v[112:113], v[162:163], v[232:233]
	v_lshlrev_b64 v[204:205], 12, v[96:97]
	v_or_b32_e32 v112, 48, v178
	global_store_dwordx4 v[206:207], v[124:127], off
	global_store_dwordx4 v[206:207], v[120:123], off offset:64
	global_store_dwordx4 v[108:109], v[104:107], off offset:64
	global_store_dwordx4 v[108:109], v[100:103], off offset:512
	v_lshl_add_u64 v[108:109], v[174:175], 0, v[204:205]
	v_ashrrev_i32_e32 v113, 31, v112
	global_load_dwordx4 v[96:99], v[108:109], off
	global_load_dwordx4 v[100:103], v[108:109], off offset:64
	global_load_dwordx4 v[104:107], v[108:109], off offset:512
	s_nop 0
	global_load_dwordx4 v[108:111], v[108:109], off offset:576
	v_lshlrev_b64 v[178:179], 12, v[112:113]
	v_lshl_add_u64 v[124:125], v[174:175], 0, v[178:179]
	global_load_dwordx4 v[112:115], v[124:125], off
	global_load_dwordx4 v[116:119], v[124:125], off offset:64
	global_load_dwordx4 v[120:123], v[124:125], off offset:512
	s_nop 0
	global_load_dwordx4 v[124:127], v[124:125], off offset:576
	s_waitcnt vmcnt(7)
	v_pk_fma_f32 v[92:93], v[92:93], v[158:159], v[96:97]
	v_lshl_add_u64 v[96:97], s[0:1], 0, v[204:205]
	v_lshl_add_u64 v[96:97], v[96:97], 0, v[172:173]
	s_waitcnt vmcnt(5)
	v_pk_fma_f32 v[78:79], v[78:79], v[164:165], v[106:107]
	v_pk_fma_f32 v[76:77], v[76:77], v[166:167], v[104:105]
	global_store_dwordx4 v[96:97], v[76:79], off offset:512
	s_waitcnt vmcnt(5)
	v_pk_fma_f32 v[74:75], v[74:75], v[168:169], v[110:111]
	v_pk_fma_f32 v[72:73], v[72:73], v[170:171], v[108:109]
	v_lshl_add_u64 v[76:77], s[0:1], 0, v[178:179]
	v_pk_fma_f32 v[94:95], v[94:95], v[156:157], v[98:99]
	v_pk_fma_f32 v[90:91], v[90:91], v[160:161], v[102:103]
	v_pk_fma_f32 v[88:89], v[88:89], v[162:163], v[100:101]
	global_store_dwordx4 v[96:97], v[72:75], off offset:576
	v_lshl_add_u64 v[76:77], v[76:77], 0, v[172:173]
	global_store_dwordx4 v[96:97], v[92:95], off
	s_waitcnt vmcnt(6)
	v_pk_fma_f32 v[74:75], v[86:87], v[156:157], v[114:115]
	v_pk_fma_f32 v[72:73], v[84:85], v[158:159], v[112:113]
	global_store_dwordx4 v[96:97], v[88:91], off offset:64
	global_store_dwordx4 v[76:77], v[72:75], off
	s_waitcnt vmcnt(6)
	v_pk_fma_f32 v[70:71], v[70:71], v[164:165], v[122:123]
	v_pk_fma_f32 v[68:69], v[68:69], v[166:167], v[120:121]
	v_pk_fma_f32 v[74:75], v[82:83], v[160:161], v[118:119]
	v_pk_fma_f32 v[72:73], v[80:81], v[162:163], v[116:117]
	s_waitcnt vmcnt(5)
	v_pk_fma_f32 v[66:67], v[66:67], v[168:169], v[126:127]
	v_pk_fma_f32 v[64:65], v[64:65], v[170:171], v[124:125]
	v_lshl_add_u64 v[96:97], v[176:177], 0, s[20:21]
	global_store_dwordx4 v[76:77], v[72:75], off offset:64
	global_store_dwordx4 v[76:77], v[68:71], off offset:512
	global_store_dwordx4 v[76:77], v[64:67], off offset:576
	v_lshl_add_u64 v[76:77], v[174:175], 0, v[96:97]
	global_load_dwordx4 v[64:67], v[76:77], off
	global_load_dwordx4 v[68:71], v[76:77], off offset:64
	global_load_dwordx4 v[72:75], v[76:77], off offset:512
	s_nop 0
	global_load_dwordx4 v[76:79], v[76:77], off offset:576
	v_lshl_add_u64 v[98:99], v[176:177], 0, s[22:23]
	v_lshl_add_u64 v[92:93], v[174:175], 0, v[98:99]
	global_load_dwordx4 v[80:83], v[92:93], off
	global_load_dwordx4 v[84:87], v[92:93], off offset:64
	global_load_dwordx4 v[88:91], v[92:93], off offset:512
	s_nop 0
	global_load_dwordx4 v[92:95], v[92:93], off offset:576
	s_waitcnt vmcnt(7)
	v_pk_fma_f32 v[60:61], v[60:61], v[158:159], v[64:65]
	v_lshl_add_u64 v[64:65], s[0:1], 0, v[96:97]
	v_lshl_add_u64 v[64:65], v[64:65], 0, v[172:173]
	s_waitcnt vmcnt(5)
	v_pk_fma_f32 v[46:47], v[46:47], v[164:165], v[74:75]
	v_pk_fma_f32 v[44:45], v[44:45], v[166:167], v[72:73]
	global_store_dwordx4 v[64:65], v[44:47], off offset:512
	s_waitcnt vmcnt(5)
	v_pk_fma_f32 v[42:43], v[42:43], v[168:169], v[78:79]
	v_pk_fma_f32 v[40:41], v[40:41], v[170:171], v[76:77]
	v_lshl_add_u64 v[44:45], s[0:1], 0, v[98:99]
	global_store_dwordx4 v[64:65], v[40:43], off offset:576
	v_lshl_add_u64 v[44:45], v[44:45], 0, v[172:173]
	v_pk_fma_f32 v[62:63], v[62:63], v[156:157], v[66:67]
	s_waitcnt vmcnt(5)
	v_pk_fma_f32 v[42:43], v[54:55], v[156:157], v[82:83]
	v_pk_fma_f32 v[40:41], v[52:53], v[158:159], v[80:81]
	v_pk_fma_f32 v[58:59], v[58:59], v[160:161], v[70:71]
	v_pk_fma_f32 v[56:57], v[56:57], v[162:163], v[68:69]
	global_store_dwordx4 v[44:45], v[40:43], off
	s_waitcnt vmcnt(4)
	v_pk_fma_f32 v[38:39], v[38:39], v[164:165], v[90:91]
	v_pk_fma_f32 v[36:37], v[36:37], v[166:167], v[88:89]
	v_pk_fma_f32 v[42:43], v[50:51], v[160:161], v[86:87]
	v_pk_fma_f32 v[40:41], v[48:49], v[162:163], v[84:85]
	s_waitcnt vmcnt(3)
	v_pk_fma_f32 v[34:35], v[34:35], v[168:169], v[94:95]
	v_pk_fma_f32 v[32:33], v[32:33], v[170:171], v[92:93]
	v_lshl_add_u64 v[66:67], v[176:177], 0, s[24:25]
	global_store_dwordx4 v[64:65], v[60:63], off
	global_store_dwordx4 v[64:65], v[56:59], off offset:64
	global_store_dwordx4 v[44:45], v[40:43], off offset:64
	global_store_dwordx4 v[44:45], v[36:39], off offset:512
	global_store_dwordx4 v[44:45], v[32:35], off offset:576
	v_lshl_add_u64 v[64:65], v[176:177], 0, s[26:27]
	v_lshl_add_u64 v[36:37], v[174:175], 0, v[64:65]
	v_lshl_add_u64 v[32:33], v[174:175], 0, v[66:67]
	global_load_dwordx4 v[48:51], v[32:33], off
	global_load_dwordx4 v[60:63], v[32:33], off offset:64
	global_load_dwordx4 v[56:59], v[32:33], off offset:512
	global_load_dwordx4 v[52:55], v[32:33], off offset:576
	s_nop 0
	global_load_dwordx4 v[32:35], v[36:37], off
	global_load_dwordx4 v[44:47], v[36:37], off offset:64
	global_load_dwordx4 v[40:43], v[36:37], off offset:512
	s_nop 0
	global_load_dwordx4 v[36:39], v[36:37], off offset:576
	s_waitcnt vmcnt(7)
	v_pk_fma_f32 v[28:29], v[28:29], v[158:159], v[48:49]
	v_lshl_add_u64 v[48:49], s[0:1], 0, v[66:67]
	v_lshl_add_u64 v[48:49], v[48:49], 0, v[172:173]
	s_waitcnt vmcnt(5)
	v_pk_fma_f32 v[18:19], v[18:19], v[164:165], v[58:59]
	v_pk_fma_f32 v[16:17], v[16:17], v[166:167], v[56:57]
	global_store_dwordx4 v[48:49], v[16:19], off offset:512
	s_waitcnt vmcnt(5)
	v_pk_fma_f32 v[10:11], v[10:11], v[168:169], v[54:55]
	v_pk_fma_f32 v[8:9], v[8:9], v[170:171], v[52:53]
	v_lshl_add_u64 v[16:17], s[0:1], 0, v[64:65]
	global_store_dwordx4 v[48:49], v[8:11], off offset:576
	v_lshl_add_u64 v[16:17], v[16:17], 0, v[172:173]
	v_pk_fma_f32 v[30:31], v[30:31], v[156:157], v[50:51]
	s_waitcnt vmcnt(5)
	v_pk_fma_f32 v[10:11], v[22:23], v[156:157], v[34:35]
	v_pk_fma_f32 v[8:9], v[20:21], v[158:159], v[32:33]
	v_pk_fma_f32 v[26:27], v[26:27], v[160:161], v[62:63]
	v_pk_fma_f32 v[24:25], v[24:25], v[162:163], v[60:61]
	global_store_dwordx4 v[16:17], v[8:11], off
	s_waitcnt vmcnt(4)
	v_pk_fma_f32 v[6:7], v[6:7], v[164:165], v[42:43]
	v_pk_fma_f32 v[4:5], v[4:5], v[166:167], v[40:41]
	v_pk_fma_f32 v[10:11], v[14:15], v[160:161], v[46:47]
	v_pk_fma_f32 v[8:9], v[12:13], v[162:163], v[44:45]
	s_waitcnt vmcnt(3)
	v_pk_fma_f32 v[2:3], v[2:3], v[168:169], v[38:39]
	v_pk_fma_f32 v[0:1], v[0:1], v[170:171], v[36:37]
	global_store_dwordx4 v[48:49], v[28:31], off
	global_store_dwordx4 v[48:49], v[24:27], off offset:64
	global_store_dwordx4 v[16:17], v[8:11], off offset:64
	global_store_dwordx4 v[16:17], v[4:7], off offset:512
	global_store_dwordx4 v[16:17], v[0:3], off offset:576
	s_waitcnt vmcnt(0)
	s_barrier
	s_and_saveexec_b64 s[46:47], s[4:5]
	s_cbranch_execz .LBB0_1188
	s_lshl_b32 s48, s44, 2
	s_ashr_i32 s49, s48, 31
	s_lshl_b64 s[48:49], s[48:49], 2
	s_add_u32 s48, s72, s48
	s_addc_u32 s49, s73, s49
	s_getreg_b32 s45, hwreg(HW_REG_XCC_ID, 0, 4)
	global_load_dwordx4 v[0:3], v131, s[48:49]
	s_and_b32 s45, s45, 15
	s_add_i32 s45, s45, 1
	s_waitcnt vmcnt(0)
	v_cmp_ne_u32_e32 vcc, s45, v2
	s_nop 1
	v_cndmask_b32_e64 v2, 0, 1, vcc
	v_cmp_ne_u32_e32 vcc, s45, v3
	v_lshlrev_b32_e32 v2, 2, v2
	s_nop 0
	v_cndmask_b32_e64 v3, 0, 1, vcc
	v_cmp_ne_u32_e32 vcc, s45, v1
	v_lshlrev_b32_e32 v3, 3, v3
	v_or_b32_e32 v2, v3, v2
	v_cndmask_b32_e64 v1, 0, 1, vcc
	v_cmp_ne_u32_e32 vcc, s45, v0
	v_lshlrev_b32_e32 v1, 1, v1
	s_nop 0
	v_cndmask_b32_e64 v0, 0, 1, vcc
	v_or_b32_e32 v0, v0, v1
	v_and_b32_e32 v0, 3, v0
	v_or_b32_e32 v0, v0, v2
	v_and_b32_e32 v0, 15, v0
	v_cmp_eq_u32_e32 vcc, 0, v0
	s_cbranch_vccnz .LBB0_1177
	buffer_wbl2 sc1
	s_waitcnt vmcnt(0)

.LBB0_1484:
	v_lshl_or_b32 v172, s66, 8, v198
	v_add_u32_e32 v156, 0x2000, v172
	v_ashrrev_i32_e32 v157, 31, v156
	v_lshlrev_b64 v[160:161], 2, v[156:157]
	s_ashr_i32 s69, s67, 3
	v_lshl_add_u64 v[164:165], s[14:15], 0, v[160:161]
	v_lshl_add_u64 v[156:157], s[16:17], 0, v[160:161]
	v_mad_i64_i32 v[160:161], s[70:71], s69, v211, v[164:165]
	global_load_dwordx4 v[156:159], v[156:157], off
	s_add_i32 s42, s69, 8
	s_add_i32 s41, s69, 16
	s_add_i32 s40, s69, 24
	s_add_i32 s39, s69, 32
	s_add_i32 s38, s69, 40
	s_add_i32 s37, s69, 48
	s_add_i32 s36, s69, 56
	s_lshl_b32 s68, s67, 8
	global_load_dwordx4 v[160:163], v[160:161], off
	v_mad_i64_i32 v[212:213], s[70:71], s42, v211, v[164:165]
	global_load_dwordx4 v[212:215], v[212:213], off
	v_mad_i64_i32 v[216:217], s[70:71], s41, v211, v[164:165]
	global_load_dwordx4 v[216:219], v[216:217], off
	v_mad_i64_i32 v[220:221], s[70:71], s40, v211, v[164:165]
	global_load_dwordx4 v[220:223], v[220:221], off
	v_mad_i64_i32 v[224:225], s[70:71], s39, v211, v[164:165]
	global_load_dwordx4 v[224:227], v[224:225], off
	v_mad_i64_i32 v[228:229], s[70:71], s38, v211, v[164:165]
	global_load_dwordx4 v[228:231], v[228:229], off
	v_mad_i64_i32 v[232:233], s[70:71], s37, v211, v[164:165]
	global_load_dwordx4 v[232:235], v[232:233], off
	v_mad_i64_i32 v[236:237], s[70:71], s36, v211, v[164:165]
	global_load_dwordx4 v[236:239], v[236:237], off
	v_ashrrev_i32_e32 v173, 31, v172
	s_waitcnt vmcnt(7)
	v_pk_add_f32 v[160:161], v[156:157], v[160:161]
	v_pk_add_f32 v[162:163], v[158:159], v[162:163]
	s_waitcnt vmcnt(6)
	v_pk_add_f32 v[160:161], v[160:161], v[212:213]
	v_pk_add_f32 v[162:163], v[162:163], v[214:215]
	s_waitcnt vmcnt(5)
	v_pk_add_f32 v[160:161], v[160:161], v[216:217]
	v_pk_add_f32 v[162:163], v[162:163], v[218:219]
	s_waitcnt vmcnt(4)
	v_pk_add_f32 v[160:161], v[160:161], v[220:221]
	v_pk_add_f32 v[162:163], v[162:163], v[222:223]
	s_waitcnt vmcnt(3)
	v_pk_add_f32 v[160:161], v[160:161], v[224:225]
	v_pk_add_f32 v[162:163], v[162:163], v[226:227]
	s_waitcnt vmcnt(2)
	v_pk_add_f32 v[160:161], v[160:161], v[228:229]
	v_pk_add_f32 v[162:163], v[162:163], v[230:231]
	s_waitcnt vmcnt(1)
	v_pk_add_f32 v[160:161], v[160:161], v[232:233]
	v_pk_add_f32 v[162:163], v[162:163], v[234:235]
	s_waitcnt vmcnt(0)
	v_pk_add_f32 v[158:159], v[162:163], v[238:239]
	v_pk_add_f32 v[160:161], v[160:161], v[236:237]
	v_pk_mul_f32 v[156:157], v[158:159], 0.5 op_sel_hi:[1, 0]
	v_pk_mul_f32 v[158:159], v[160:161], 0.5 op_sel_hi:[1, 0]
	v_add_u32_e32 v160, 0x2010, v172
	v_ashrrev_i32_e32 v161, 31, v160
	v_lshlrev_b64 v[164:165], 2, v[160:161]
	v_lshl_add_u64 v[168:169], s[14:15], 0, v[164:165]
	v_lshl_add_u64 v[160:161], s[16:17], 0, v[164:165]
	v_mad_i64_i32 v[164:165], s[70:71], s69, v211, v[168:169]
	global_load_dwordx4 v[160:163], v[160:161], off
	global_load_dwordx4 v[164:167], v[164:165], off
	v_mad_i64_i32 v[212:213], s[70:71], s42, v211, v[168:169]
	global_load_dwordx4 v[212:215], v[212:213], off
	v_mad_i64_i32 v[216:217], s[70:71], s41, v211, v[168:169]
	global_load_dwordx4 v[216:219], v[216:217], off
	v_mad_i64_i32 v[220:221], s[70:71], s40, v211, v[168:169]
	global_load_dwordx4 v[220:223], v[220:221], off
	v_mad_i64_i32 v[224:225], s[70:71], s39, v211, v[168:169]
	global_load_dwordx4 v[224:227], v[224:225], off
	v_mad_i64_i32 v[228:229], s[70:71], s38, v211, v[168:169]
	global_load_dwordx4 v[228:231], v[228:229], off
	v_mad_i64_i32 v[232:233], s[70:71], s37, v211, v[168:169]
	global_load_dwordx4 v[232:235], v[232:233], off
	v_mad_i64_i32 v[236:237], s[70:71], s36, v211, v[168:169]
	global_load_dwordx4 v[236:239], v[236:237], off
	s_waitcnt vmcnt(7)
	v_pk_add_f32 v[164:165], v[160:161], v[164:165]
	v_pk_add_f32 v[166:167], v[162:163], v[166:167]
	s_waitcnt vmcnt(6)
	v_pk_add_f32 v[164:165], v[164:165], v[212:213]
	v_pk_add_f32 v[166:167], v[166:167], v[214:215]
	s_waitcnt vmcnt(5)
	v_pk_add_f32 v[164:165], v[164:165], v[216:217]
	v_pk_add_f32 v[166:167], v[166:167], v[218:219]
	s_waitcnt vmcnt(4)
	v_pk_add_f32 v[164:165], v[164:165], v[220:221]
	v_pk_add_f32 v[166:167], v[166:167], v[222:223]
	s_waitcnt vmcnt(3)
	v_pk_add_f32 v[164:165], v[164:165], v[224:225]
	v_pk_add_f32 v[166:167], v[166:167], v[226:227]
	s_waitcnt vmcnt(2)
	v_pk_add_f32 v[164:165], v[164:165], v[228:229]
	v_pk_add_f32 v[166:167], v[166:167], v[230:231]
	s_waitcnt vmcnt(1)
	v_pk_add_f32 v[164:165], v[164:165], v[232:233]
	v_pk_add_f32 v[166:167], v[166:167], v[234:235]
	s_waitcnt vmcnt(0)
	v_pk_add_f32 v[162:163], v[166:167], v[238:239]
	v_pk_add_f32 v[164:165], v[164:165], v[236:237]
	v_pk_mul_f32 v[160:161], v[162:163], 0.5 op_sel_hi:[1, 0]
	v_pk_mul_f32 v[162:163], v[164:165], 0.5 op_sel_hi:[1, 0]
	v_add_u32_e32 v164, 0x2080, v172
	v_ashrrev_i32_e32 v165, 31, v164
	v_lshlrev_b64 v[168:169], 2, v[164:165]
	v_lshl_add_u64 v[174:175], s[14:15], 0, v[168:169]
	v_lshl_add_u64 v[164:165], s[16:17], 0, v[168:169]
	v_mad_i64_i32 v[168:169], s[70:71], s69, v211, v[174:175]
	global_load_dwordx4 v[164:167], v[164:165], off
	global_load_dwordx4 v[168:171], v[168:169], off
	v_mad_i64_i32 v[212:213], s[70:71], s42, v211, v[174:175]
	global_load_dwordx4 v[212:215], v[212:213], off
	v_mad_i64_i32 v[216:217], s[70:71], s41, v211, v[174:175]
	global_load_dwordx4 v[216:219], v[216:217], off
	v_mad_i64_i32 v[220:221], s[70:71], s40, v211, v[174:175]
	global_load_dwordx4 v[220:223], v[220:221], off
	v_mad_i64_i32 v[224:225], s[70:71], s39, v211, v[174:175]
	global_load_dwordx4 v[224:227], v[224:225], off
	v_mad_i64_i32 v[228:229], s[70:71], s38, v211, v[174:175]
	global_load_dwordx4 v[228:231], v[228:229], off
	v_mad_i64_i32 v[232:233], s[70:71], s37, v211, v[174:175]
	global_load_dwordx4 v[232:235], v[232:233], off
	v_mad_i64_i32 v[236:237], s[70:71], s36, v211, v[174:175]
	global_load_dwordx4 v[236:239], v[236:237], off
	s_waitcnt vmcnt(7)
	v_pk_add_f32 v[168:169], v[164:165], v[168:169]
	v_pk_add_f32 v[170:171], v[166:167], v[170:171]
	s_waitcnt vmcnt(6)
	v_pk_add_f32 v[168:169], v[168:169], v[212:213]
	v_pk_add_f32 v[170:171], v[170:171], v[214:215]
	s_waitcnt vmcnt(5)
	v_pk_add_f32 v[168:169], v[168:169], v[216:217]
	v_pk_add_f32 v[170:171], v[170:171], v[218:219]
	s_waitcnt vmcnt(4)
	v_pk_add_f32 v[168:169], v[168:169], v[220:221]
	v_pk_add_f32 v[170:171], v[170:171], v[222:223]
	s_waitcnt vmcnt(3)
	v_pk_add_f32 v[168:169], v[168:169], v[224:225]
	v_pk_add_f32 v[170:171], v[170:171], v[226:227]
	s_waitcnt vmcnt(2)
	v_pk_add_f32 v[168:169], v[168:169], v[228:229]
	v_pk_add_f32 v[170:171], v[170:171], v[230:231]
	s_waitcnt vmcnt(1)
	v_pk_add_f32 v[168:169], v[168:169], v[232:233]
	v_pk_add_f32 v[170:171], v[170:171], v[234:235]
	s_waitcnt vmcnt(0)
	v_pk_add_f32 v[166:167], v[170:171], v[238:239]
	v_pk_add_f32 v[168:169], v[168:169], v[236:237]
	v_pk_mul_f32 v[164:165], v[166:167], 0.5 op_sel_hi:[1, 0]
	v_pk_mul_f32 v[166:167], v[168:169], 0.5 op_sel_hi:[1, 0]
	v_add_u32_e32 v168, 0x2090, v172
	v_ashrrev_i32_e32 v169, 31, v168
	v_lshlrev_b64 v[174:175], 2, v[168:169]
	v_lshl_add_u64 v[178:179], s[14:15], 0, v[174:175]
	v_lshl_add_u64 v[168:169], s[16:17], 0, v[174:175]
	v_mad_i64_i32 v[174:175], s[70:71], s69, v211, v[178:179]
	global_load_dwordx4 v[168:171], v[168:169], off
	global_load_dwordx4 v[174:177], v[174:175], off
	v_mad_i64_i32 v[212:213], s[42:43], s42, v211, v[178:179]
	global_load_dwordx4 v[212:215], v[212:213], off
	v_mad_i64_i32 v[216:217], s[42:43], s41, v211, v[178:179]
	global_load_dwordx4 v[216:219], v[216:217], off
	v_mad_i64_i32 v[220:221], s[40:41], s40, v211, v[178:179]
	global_load_dwordx4 v[220:223], v[220:221], off
	v_mad_i64_i32 v[224:225], s[40:41], s39, v211, v[178:179]
	global_load_dwordx4 v[224:227], v[224:225], off
	v_mad_i64_i32 v[228:229], s[38:39], s38, v211, v[178:179]
	global_load_dwordx4 v[228:231], v[228:229], off
	v_mad_i64_i32 v[232:233], s[38:39], s37, v211, v[178:179]
	global_load_dwordx4 v[232:235], v[232:233], off
	v_mad_i64_i32 v[236:237], s[36:37], s36, v211, v[178:179]
	global_load_dwordx4 v[236:239], v[236:237], off
	v_lshlrev_b64 v[172:173], 2, v[172:173]
	v_readfirstlane_b32 s70, v180
	s_waitcnt vmcnt(7)
	v_pk_add_f32 v[174:175], v[168:169], v[174:175]
	v_pk_add_f32 v[176:177], v[170:171], v[176:177]
	s_waitcnt vmcnt(6)
	v_pk_add_f32 v[174:175], v[174:175], v[212:213]
	v_pk_add_f32 v[176:177], v[176:177], v[214:215]
	s_waitcnt vmcnt(5)
	v_pk_add_f32 v[174:175], v[174:175], v[216:217]
	v_pk_add_f32 v[176:177], v[176:177], v[218:219]
	s_waitcnt vmcnt(4)
	v_pk_add_f32 v[174:175], v[174:175], v[220:221]
	v_pk_add_f32 v[176:177], v[176:177], v[222:223]
	s_waitcnt vmcnt(3)
	v_pk_add_f32 v[174:175], v[174:175], v[224:225]
	v_pk_add_f32 v[176:177], v[176:177], v[226:227]
	s_waitcnt vmcnt(2)
	v_pk_add_f32 v[174:175], v[174:175], v[228:229]
	v_pk_add_f32 v[176:177], v[176:177], v[230:231]
	s_waitcnt vmcnt(1)
	v_pk_add_f32 v[174:175], v[174:175], v[232:233]
	v_pk_add_f32 v[176:177], v[176:177], v[234:235]
	v_add_u32_e32 v178, s68, v181
	v_ashrrev_i32_e32 v179, 31, v178
	s_waitcnt vmcnt(0)
	v_pk_add_f32 v[170:171], v[176:177], v[238:239]
	v_pk_add_f32 v[174:175], v[174:175], v[236:237]
	v_pk_mul_f32 v[168:169], v[170:171], 0.5 op_sel_hi:[1, 0]
	v_pk_mul_f32 v[170:171], v[174:175], 0.5 op_sel_hi:[1, 0]
	v_lshl_add_u64 v[174:175], s[12:13], 0, v[172:173]
	v_lshlrev_b64 v[176:177], 12, v[178:179]
	v_lshl_add_u64 v[204:205], v[174:175], 0, v[176:177]
	v_mbcnt_lo_u32_b32 v180, -1, 0
	v_mbcnt_hi_u32_b32 v180, -1, v180
	v_lshrrev_b32_e32 v180, 4, v180
	v_and_b32_e32 v181, 1, v180
	v_lshlrev_b32_e32 v181, 16, v181
	v_lshrrev_b32_e32 v184, 1, v180
	v_lshl_add_u32 v181, v184, 9, v181
	v_lshlrev_b32_e32 v180, 4, v180
	v_sub_u32_e32 v180, v181, v180
	v_mov_b32_e32 v181, 0
	v_lshl_add_u64 v[180:181], v[204:205], 0, v[180:181]
	v_mov_b32_e32 v186, 0x20000
	v_mov_b32_e32 v187, 0
	v_lshl_add_u64 v[184:185], v[180:181], 0, v[186:187]
	global_load_dword v182, v[184:185], off
	v_mov_b32_e32 v186, 0x60000
	v_lshl_add_u64 v[184:185], v[184:185], 0, v[186:187]
	global_load_dword v182, v[184:185], off
	v_mov_b32_e32 v186, 0x20000
	v_lshl_add_u64 v[184:185], v[184:185], 0, v[186:187]
	global_load_dword v182, v[184:185], off
	global_load_dwordx4 v[212:215], v[204:205], off
	global_load_dwordx4 v[216:219], v[204:205], off offset:64
	global_load_dwordx4 v[220:223], v[204:205], off offset:512
	global_load_dwordx4 v[224:227], v[204:205], off offset:576
	v_or_b32_e32 v204, 16, v178
	v_ashrrev_i32_e32 v205, 31, v204
	v_lshlrev_b64 v[204:205], 12, v[204:205]
	v_lshl_add_u64 v[206:207], v[174:175], 0, v[204:205]
	global_load_dwordx4 v[228:231], v[206:207], off
	global_load_dwordx4 v[232:235], v[206:207], off offset:64
	global_load_dwordx4 v[236:239], v[206:207], off offset:512
	global_load_dwordx4 v[240:243], v[206:207], off offset:576
	v_lshl_add_u64 v[206:207], s[12:13], 0, v[176:177]
	v_lshl_add_u64 v[206:207], v[206:207], 0, v[172:173]
	s_waitcnt vmcnt(7)
	v_pk_fma_f32 v[126:127], v[126:127], v[156:157], v[214:215]
	v_pk_fma_f32 v[124:125], v[124:125], v[158:159], v[212:213]
	s_waitcnt vmcnt(5)
	v_pk_fma_f32 v[110:111], v[110:111], v[164:165], v[222:223]
	v_pk_fma_f32 v[108:109], v[108:109], v[166:167], v[220:221]
	global_store_dwordx4 v[206:207], v[108:111], off offset:512
	s_waitcnt vmcnt(5)
	v_pk_fma_f32 v[106:107], v[106:107], v[168:169], v[226:227]
	v_pk_fma_f32 v[104:105], v[104:105], v[170:171], v[224:225]
	v_lshl_add_u64 v[108:109], s[12:13], 0, v[204:205]
	v_lshl_add_u64 v[108:109], v[108:109], 0, v[172:173]
	s_waitcnt vmcnt(1)
	v_pk_fma_f32 v[98:99], v[98:99], v[168:169], v[242:243]
	v_pk_fma_f32 v[96:97], v[96:97], v[170:171], v[240:241]
	global_store_dwordx4 v[108:109], v[96:99], off offset:576
	global_store_dwordx4 v[206:207], v[104:107], off offset:576
	v_pk_fma_f32 v[122:123], v[122:123], v[160:161], v[218:219]
	v_or_b32_e32 v96, 32, v178
	v_pk_fma_f32 v[106:107], v[118:119], v[156:157], v[230:231]
	v_pk_fma_f32 v[104:105], v[116:117], v[158:159], v[228:229]
	v_ashrrev_i32_e32 v97, 31, v96
	v_pk_fma_f32 v[120:121], v[120:121], v[162:163], v[216:217]
	global_store_dwordx4 v[108:109], v[104:107], off
	v_pk_fma_f32 v[102:103], v[102:103], v[164:165], v[238:239]
	v_pk_fma_f32 v[100:101], v[100:101], v[166:167], v[236:237]
	v_pk_fma_f32 v[106:107], v[114:115], v[160:161], v[234:235]
	v_pk_fma_f32 v[104:105], v[112:113], v[162:163], v[232:233]
	v_lshlrev_b64 v[204:205], 12, v[96:97]
	v_or_b32_e32 v112, 48, v178
	global_store_dwordx4 v[206:207], v[124:127], off
	global_store_dwordx4 v[206:207], v[120:123], off offset:64
	global_store_dwordx4 v[108:109], v[104:107], off offset:64
	global_store_dwordx4 v[108:109], v[100:103], off offset:512
	v_lshl_add_u64 v[108:109], v[174:175], 0, v[204:205]
	v_ashrrev_i32_e32 v113, 31, v112
	global_load_dwordx4 v[96:99], v[108:109], off
	global_load_dwordx4 v[100:103], v[108:109], off offset:64
	global_load_dwordx4 v[104:107], v[108:109], off offset:512
	s_nop 0
	global_load_dwordx4 v[108:111], v[108:109], off offset:576
	v_lshlrev_b64 v[178:179], 12, v[112:113]
	v_lshl_add_u64 v[124:125], v[174:175], 0, v[178:179]
	global_load_dwordx4 v[112:115], v[124:125], off
	global_load_dwordx4 v[116:119], v[124:125], off offset:64
	global_load_dwordx4 v[120:123], v[124:125], off offset:512
	s_nop 0
	global_load_dwordx4 v[124:127], v[124:125], off offset:576
	s_waitcnt vmcnt(7)
	v_pk_fma_f32 v[92:93], v[92:93], v[158:159], v[96:97]
	v_lshl_add_u64 v[96:97], s[12:13], 0, v[204:205]
	v_lshl_add_u64 v[96:97], v[96:97], 0, v[172:173]
	s_waitcnt vmcnt(5)
	v_pk_fma_f32 v[78:79], v[78:79], v[164:165], v[106:107]
	v_pk_fma_f32 v[76:77], v[76:77], v[166:167], v[104:105]
	global_store_dwordx4 v[96:97], v[76:79], off offset:512
	s_waitcnt vmcnt(5)
	v_pk_fma_f32 v[74:75], v[74:75], v[168:169], v[110:111]
	v_pk_fma_f32 v[72:73], v[72:73], v[170:171], v[108:109]
	v_lshl_add_u64 v[76:77], s[12:13], 0, v[178:179]
	v_pk_fma_f32 v[94:95], v[94:95], v[156:157], v[98:99]
	v_pk_fma_f32 v[90:91], v[90:91], v[160:161], v[102:103]
	v_pk_fma_f32 v[88:89], v[88:89], v[162:163], v[100:101]
	global_store_dwordx4 v[96:97], v[72:75], off offset:576
	v_lshl_add_u64 v[76:77], v[76:77], 0, v[172:173]
	global_store_dwordx4 v[96:97], v[92:95], off
	s_waitcnt vmcnt(6)
	v_pk_fma_f32 v[74:75], v[86:87], v[156:157], v[114:115]
	v_pk_fma_f32 v[72:73], v[84:85], v[158:159], v[112:113]
	global_store_dwordx4 v[96:97], v[88:91], off offset:64
	global_store_dwordx4 v[76:77], v[72:75], off
	s_waitcnt vmcnt(6)
	v_pk_fma_f32 v[70:71], v[70:71], v[164:165], v[122:123]
	v_pk_fma_f32 v[68:69], v[68:69], v[166:167], v[120:121]
	v_pk_fma_f32 v[74:75], v[82:83], v[160:161], v[118:119]
	v_pk_fma_f32 v[72:73], v[80:81], v[162:163], v[116:117]
	s_waitcnt vmcnt(5)
	v_pk_fma_f32 v[66:67], v[66:67], v[168:169], v[126:127]
	v_pk_fma_f32 v[64:65], v[64:65], v[170:171], v[124:125]
	v_lshl_add_u64 v[96:97], v[176:177], 0, s[20:21]
	global_store_dwordx4 v[76:77], v[72:75], off offset:64
	global_store_dwordx4 v[76:77], v[68:71], off offset:512
	global_store_dwordx4 v[76:77], v[64:67], off offset:576
	v_lshl_add_u64 v[76:77], v[174:175], 0, v[96:97]
	global_load_dwordx4 v[64:67], v[76:77], off
	global_load_dwordx4 v[68:71], v[76:77], off offset:64
	global_load_dwordx4 v[72:75], v[76:77], off offset:512
	s_nop 0
	global_load_dwordx4 v[76:79], v[76:77], off offset:576
	v_lshl_add_u64 v[98:99], v[176:177], 0, s[22:23]
	v_lshl_add_u64 v[92:93], v[174:175], 0, v[98:99]
	global_load_dwordx4 v[80:83], v[92:93], off
	global_load_dwordx4 v[84:87], v[92:93], off offset:64
	global_load_dwordx4 v[88:91], v[92:93], off offset:512
	s_nop 0
	global_load_dwordx4 v[92:95], v[92:93], off offset:576
	s_waitcnt vmcnt(7)
	v_pk_fma_f32 v[60:61], v[60:61], v[158:159], v[64:65]
	v_lshl_add_u64 v[64:65], s[12:13], 0, v[96:97]
	v_lshl_add_u64 v[64:65], v[64:65], 0, v[172:173]
	s_waitcnt vmcnt(5)
	v_pk_fma_f32 v[46:47], v[46:47], v[164:165], v[74:75]
	v_pk_fma_f32 v[44:45], v[44:45], v[166:167], v[72:73]
	global_store_dwordx4 v[64:65], v[44:47], off offset:512
	s_waitcnt vmcnt(5)
	v_pk_fma_f32 v[42:43], v[42:43], v[168:169], v[78:79]
	v_pk_fma_f32 v[40:41], v[40:41], v[170:171], v[76:77]
	v_lshl_add_u64 v[44:45], s[12:13], 0, v[98:99]
	v_pk_fma_f32 v[62:63], v[62:63], v[156:157], v[66:67]
	v_pk_fma_f32 v[58:59], v[58:59], v[160:161], v[70:71]
	v_pk_fma_f32 v[56:57], v[56:57], v[162:163], v[68:69]
	global_store_dwordx4 v[64:65], v[40:43], off offset:576
	v_lshl_add_u64 v[44:45], v[44:45], 0, v[172:173]
	global_store_dwordx4 v[64:65], v[60:63], off
	s_waitcnt vmcnt(6)
	v_pk_fma_f32 v[42:43], v[54:55], v[156:157], v[82:83]
	v_pk_fma_f32 v[40:41], v[52:53], v[158:159], v[80:81]
	global_store_dwordx4 v[64:65], v[56:59], off offset:64
	global_store_dwordx4 v[44:45], v[40:43], off
	s_waitcnt vmcnt(6)
	v_pk_fma_f32 v[38:39], v[38:39], v[164:165], v[90:91]
	v_pk_fma_f32 v[36:37], v[36:37], v[166:167], v[88:89]
	v_pk_fma_f32 v[42:43], v[50:51], v[160:161], v[86:87]
	v_pk_fma_f32 v[40:41], v[48:49], v[162:163], v[84:85]
	s_waitcnt vmcnt(5)
	v_pk_fma_f32 v[34:35], v[34:35], v[168:169], v[94:95]
	v_pk_fma_f32 v[32:33], v[32:33], v[170:171], v[92:93]
	v_lshl_add_u64 v[64:65], v[176:177], 0, s[24:25]
	global_store_dwordx4 v[44:45], v[40:43], off offset:64
	global_store_dwordx4 v[44:45], v[36:39], off offset:512
	global_store_dwordx4 v[44:45], v[32:35], off offset:576
	v_lshl_add_u64 v[44:45], v[174:175], 0, v[64:65]
	global_load_dwordx4 v[32:35], v[44:45], off
	global_load_dwordx4 v[36:39], v[44:45], off offset:64
	global_load_dwordx4 v[40:43], v[44:45], off offset:512
	s_nop 0
	global_load_dwordx4 v[44:47], v[44:45], off offset:576
	v_lshl_add_u64 v[66:67], v[176:177], 0, s[26:27]
	v_lshl_add_u64 v[60:61], v[174:175], 0, v[66:67]
	global_load_dwordx4 v[48:51], v[60:61], off
	global_load_dwordx4 v[52:55], v[60:61], off offset:64
	global_load_dwordx4 v[56:59], v[60:61], off offset:512
	s_nop 0
	global_load_dwordx4 v[60:63], v[60:61], off offset:576
	s_waitcnt vmcnt(7)
	v_pk_fma_f32 v[28:29], v[28:29], v[158:159], v[32:33]
	v_lshl_add_u64 v[32:33], s[12:13], 0, v[64:65]
	v_lshl_add_u64 v[32:33], v[32:33], 0, v[172:173]
	s_waitcnt vmcnt(5)
	v_pk_fma_f32 v[18:19], v[18:19], v[164:165], v[42:43]
	v_pk_fma_f32 v[16:17], v[16:17], v[166:167], v[40:41]
	global_store_dwordx4 v[32:33], v[16:19], off offset:512
	s_waitcnt vmcnt(5)
	v_pk_fma_f32 v[10:11], v[10:11], v[168:169], v[46:47]
	v_pk_fma_f32 v[8:9], v[8:9], v[170:171], v[44:45]
	v_lshl_add_u64 v[16:17], s[12:13], 0, v[66:67]
	global_store_dwordx4 v[32:33], v[8:11], off offset:576
	v_lshl_add_u64 v[16:17], v[16:17], 0, v[172:173]
	v_pk_fma_f32 v[30:31], v[30:31], v[156:157], v[34:35]
	s_waitcnt vmcnt(5)
	v_pk_fma_f32 v[10:11], v[22:23], v[156:157], v[50:51]
	v_pk_fma_f32 v[8:9], v[20:21], v[158:159], v[48:49]
	v_pk_fma_f32 v[26:27], v[26:27], v[160:161], v[38:39]
	v_pk_fma_f32 v[24:25], v[24:25], v[162:163], v[36:37]
	global_store_dwordx4 v[16:17], v[8:11], off
	s_waitcnt vmcnt(4)
	v_pk_fma_f32 v[6:7], v[6:7], v[164:165], v[58:59]
	v_pk_fma_f32 v[4:5], v[4:5], v[166:167], v[56:57]
	v_pk_fma_f32 v[10:11], v[14:15], v[160:161], v[54:55]
	v_pk_fma_f32 v[8:9], v[12:13], v[162:163], v[52:53]
	s_waitcnt vmcnt(3)
	v_pk_fma_f32 v[2:3], v[2:3], v[168:169], v[62:63]
	v_pk_fma_f32 v[0:1], v[0:1], v[170:171], v[60:61]
	global_store_dwordx4 v[32:33], v[28:31], off
	global_store_dwordx4 v[32:33], v[24:27], off offset:64
	global_store_dwordx4 v[16:17], v[8:11], off offset:64
	global_store_dwordx4 v[16:17], v[4:7], off offset:512
	global_store_dwordx4 v[16:17], v[0:3], off offset:576
	s_waitcnt vmcnt(0)
	s_barrier
	s_and_saveexec_b64 s[36:37], s[4:5]
	s_cbranch_execz .LBB0_1498
	s_lshl_b32 s38, s67, 2
	s_ashr_i32 s39, s38, 31
	s_lshl_b64 s[38:39], s[38:39], 2
	s_add_u32 s38, s55, s38
	s_addc_u32 s39, s56, s39
	s_getreg_b32 s40, hwreg(HW_REG_XCC_ID, 0, 4)
	global_load_dwordx4 v[0:3], v129, s[38:39]
	s_and_b32 s38, s40, 15
	s_add_i32 s38, s38, 1
	s_waitcnt vmcnt(0)
	v_cmp_ne_u32_e32 vcc, s38, v2
	s_nop 1
	v_cndmask_b32_e64 v2, 0, 1, vcc
	v_cmp_ne_u32_e32 vcc, s38, v3
	v_lshlrev_b32_e32 v2, 2, v2
	s_nop 0
	v_cndmask_b32_e64 v3, 0, 1, vcc
	v_cmp_ne_u32_e32 vcc, s38, v1
	v_lshlrev_b32_e32 v3, 3, v3
	v_or_b32_e32 v2, v3, v2
	v_cndmask_b32_e64 v1, 0, 1, vcc
	v_cmp_ne_u32_e32 vcc, s38, v0
	v_lshlrev_b32_e32 v1, 1, v1
	s_nop 0
	v_cndmask_b32_e64 v0, 0, 1, vcc
	v_or_b32_e32 v0, v0, v1
	v_and_b32_e32 v0, 3, v0
	v_or_b32_e32 v0, v0, v2
	v_and_b32_e32 v0, 15, v0
	v_cmp_eq_u32_e32 vcc, 0, v0
	s_cbranch_vccnz .LBB0_1487
	buffer_wbl2 sc1
	s_waitcnt vmcnt(0)

.LBB0_1648:
	v_lshl_or_b32 v172, s74, 8, v198
	v_add_u32_e32 v156, 0x800, v172
	v_ashrrev_i32_e32 v157, 31, v156
	s_ashr_i32 s48, s44, 3
	v_lshlrev_b64 v[160:161], 2, v[156:157]
	s_add_i32 s49, s48, 64
	v_lshl_add_u64 v[164:165], s[14:15], 0, v[160:161]
	v_lshl_add_u64 v[156:157], s[18:19], 0, v[160:161]
	v_mad_i64_i32 v[160:161], s[36:37], s49, v211, v[164:165]
	global_load_dwordx4 v[156:159], v[156:157], off
	s_add_i32 s47, s48, 0x48
	s_add_i32 s46, s48, 0x50
	s_add_i32 s45, s48, 0x58
	s_add_i32 s79, s48, 0x60
	s_add_i32 s78, s48, 0x68
	s_add_i32 s77, s48, 0x70
	s_add_i32 s76, s48, 0x78
	s_lshl_b32 s75, s44, 8
	global_load_dwordx4 v[160:163], v[160:161], off
	v_mad_i64_i32 v[212:213], s[36:37], s47, v211, v[164:165]
	global_load_dwordx4 v[212:215], v[212:213], off
	v_mad_i64_i32 v[216:217], s[36:37], s46, v211, v[164:165]
	global_load_dwordx4 v[216:219], v[216:217], off
	v_mad_i64_i32 v[220:221], s[36:37], s45, v211, v[164:165]
	global_load_dwordx4 v[220:223], v[220:221], off
	v_mad_i64_i32 v[224:225], s[36:37], s79, v211, v[164:165]
	global_load_dwordx4 v[224:227], v[224:225], off
	v_mad_i64_i32 v[228:229], s[36:37], s78, v211, v[164:165]
	global_load_dwordx4 v[228:231], v[228:229], off
	v_mad_i64_i32 v[232:233], s[36:37], s77, v211, v[164:165]
	global_load_dwordx4 v[232:235], v[232:233], off
	v_mad_i64_i32 v[236:237], s[36:37], s76, v211, v[164:165]
	global_load_dwordx4 v[236:239], v[236:237], off
	v_ashrrev_i32_e32 v173, 31, v172
	v_readfirstlane_b32 s80, v180
	s_waitcnt vmcnt(7)
	v_pk_add_f32 v[160:161], v[156:157], v[160:161]
	v_pk_add_f32 v[162:163], v[158:159], v[162:163]
	s_waitcnt vmcnt(6)
	v_pk_add_f32 v[160:161], v[160:161], v[212:213]
	v_pk_add_f32 v[162:163], v[162:163], v[214:215]
	s_waitcnt vmcnt(5)
	v_pk_add_f32 v[160:161], v[160:161], v[216:217]
	v_pk_add_f32 v[162:163], v[162:163], v[218:219]
	s_waitcnt vmcnt(4)
	v_pk_add_f32 v[160:161], v[160:161], v[220:221]
	v_pk_add_f32 v[162:163], v[162:163], v[222:223]
	s_waitcnt vmcnt(3)
	v_pk_add_f32 v[160:161], v[160:161], v[224:225]
	v_pk_add_f32 v[162:163], v[162:163], v[226:227]
	s_waitcnt vmcnt(2)
	v_pk_add_f32 v[160:161], v[160:161], v[228:229]
	v_pk_add_f32 v[162:163], v[162:163], v[230:231]
	s_waitcnt vmcnt(1)
	v_pk_add_f32 v[160:161], v[160:161], v[232:233]
	v_pk_add_f32 v[162:163], v[162:163], v[234:235]
	s_waitcnt vmcnt(0)
	v_pk_add_f32 v[158:159], v[162:163], v[238:239]
	v_pk_add_f32 v[160:161], v[160:161], v[236:237]
	v_pk_mul_f32 v[156:157], v[158:159], 0.5 op_sel_hi:[1, 0]
	v_pk_mul_f32 v[158:159], v[160:161], 0.5 op_sel_hi:[1, 0]
	v_add_u32_e32 v160, 0x810, v172
	v_ashrrev_i32_e32 v161, 31, v160
	v_lshlrev_b64 v[164:165], 2, v[160:161]
	v_lshl_add_u64 v[168:169], s[14:15], 0, v[164:165]
	v_lshl_add_u64 v[160:161], s[18:19], 0, v[164:165]
	v_mad_i64_i32 v[164:165], s[36:37], s49, v211, v[168:169]
	global_load_dwordx4 v[160:163], v[160:161], off
	global_load_dwordx4 v[164:167], v[164:165], off
	v_mad_i64_i32 v[212:213], s[36:37], s47, v211, v[168:169]
	global_load_dwordx4 v[212:215], v[212:213], off
	v_mad_i64_i32 v[216:217], s[36:37], s46, v211, v[168:169]
	global_load_dwordx4 v[216:219], v[216:217], off
	v_mad_i64_i32 v[220:221], s[36:37], s45, v211, v[168:169]
	global_load_dwordx4 v[220:223], v[220:221], off
	v_mad_i64_i32 v[224:225], s[36:37], s79, v211, v[168:169]
	global_load_dwordx4 v[224:227], v[224:225], off
	v_mad_i64_i32 v[228:229], s[36:37], s78, v211, v[168:169]
	global_load_dwordx4 v[228:231], v[228:229], off
	v_mad_i64_i32 v[232:233], s[36:37], s77, v211, v[168:169]
	global_load_dwordx4 v[232:235], v[232:233], off
	v_mad_i64_i32 v[236:237], s[36:37], s76, v211, v[168:169]
	global_load_dwordx4 v[236:239], v[236:237], off
	s_waitcnt vmcnt(7)
	v_pk_add_f32 v[164:165], v[160:161], v[164:165]
	v_pk_add_f32 v[166:167], v[162:163], v[166:167]
	s_waitcnt vmcnt(6)
	v_pk_add_f32 v[164:165], v[164:165], v[212:213]
	v_pk_add_f32 v[166:167], v[166:167], v[214:215]
	s_waitcnt vmcnt(5)
	v_pk_add_f32 v[164:165], v[164:165], v[216:217]
	v_pk_add_f32 v[166:167], v[166:167], v[218:219]
	s_waitcnt vmcnt(4)
	v_pk_add_f32 v[164:165], v[164:165], v[220:221]
	v_pk_add_f32 v[166:167], v[166:167], v[222:223]
	s_waitcnt vmcnt(3)
	v_pk_add_f32 v[164:165], v[164:165], v[224:225]
	v_pk_add_f32 v[166:167], v[166:167], v[226:227]
	s_waitcnt vmcnt(2)
	v_pk_add_f32 v[164:165], v[164:165], v[228:229]
	v_pk_add_f32 v[166:167], v[166:167], v[230:231]
	s_waitcnt vmcnt(1)
	v_pk_add_f32 v[164:165], v[164:165], v[232:233]
	v_pk_add_f32 v[166:167], v[166:167], v[234:235]
	s_waitcnt vmcnt(0)
	v_pk_add_f32 v[162:163], v[166:167], v[238:239]
	v_pk_add_f32 v[164:165], v[164:165], v[236:237]
	v_pk_mul_f32 v[160:161], v[162:163], 0.5 op_sel_hi:[1, 0]
	v_pk_mul_f32 v[162:163], v[164:165], 0.5 op_sel_hi:[1, 0]
	v_add_u32_e32 v164, 0x880, v172
	v_ashrrev_i32_e32 v165, 31, v164
	v_lshlrev_b64 v[168:169], 2, v[164:165]
	v_lshl_add_u64 v[174:175], s[14:15], 0, v[168:169]
	v_lshl_add_u64 v[164:165], s[18:19], 0, v[168:169]
	v_mad_i64_i32 v[168:169], s[36:37], s49, v211, v[174:175]
	global_load_dwordx4 v[164:167], v[164:165], off
	global_load_dwordx4 v[168:171], v[168:169], off
	v_mad_i64_i32 v[212:213], s[36:37], s47, v211, v[174:175]
	global_load_dwordx4 v[212:215], v[212:213], off
	v_mad_i64_i32 v[216:217], s[36:37], s46, v211, v[174:175]
	global_load_dwordx4 v[216:219], v[216:217], off
	v_mad_i64_i32 v[220:221], s[36:37], s45, v211, v[174:175]
	global_load_dwordx4 v[220:223], v[220:221], off
	v_mad_i64_i32 v[224:225], s[36:37], s79, v211, v[174:175]
	global_load_dwordx4 v[224:227], v[224:225], off
	v_mad_i64_i32 v[228:229], s[36:37], s78, v211, v[174:175]
	global_load_dwordx4 v[228:231], v[228:229], off
	v_mad_i64_i32 v[232:233], s[36:37], s77, v211, v[174:175]
	global_load_dwordx4 v[232:235], v[232:233], off
	v_mad_i64_i32 v[236:237], s[36:37], s76, v211, v[174:175]
	global_load_dwordx4 v[236:239], v[236:237], off
	s_waitcnt vmcnt(7)
	v_pk_add_f32 v[168:169], v[164:165], v[168:169]
	v_pk_add_f32 v[170:171], v[166:167], v[170:171]
	s_waitcnt vmcnt(6)
	v_pk_add_f32 v[168:169], v[168:169], v[212:213]
	v_pk_add_f32 v[170:171], v[170:171], v[214:215]
	s_waitcnt vmcnt(5)
	v_pk_add_f32 v[168:169], v[168:169], v[216:217]
	v_pk_add_f32 v[170:171], v[170:171], v[218:219]
	s_waitcnt vmcnt(4)
	v_pk_add_f32 v[168:169], v[168:169], v[220:221]
	v_pk_add_f32 v[170:171], v[170:171], v[222:223]
	s_waitcnt vmcnt(3)
	v_pk_add_f32 v[168:169], v[168:169], v[224:225]
	v_pk_add_f32 v[170:171], v[170:171], v[226:227]
	s_waitcnt vmcnt(2)
	v_pk_add_f32 v[168:169], v[168:169], v[228:229]
	v_pk_add_f32 v[170:171], v[170:171], v[230:231]
	s_waitcnt vmcnt(1)
	v_pk_add_f32 v[168:169], v[168:169], v[232:233]
	v_pk_add_f32 v[170:171], v[170:171], v[234:235]
	s_waitcnt vmcnt(0)
	v_pk_add_f32 v[166:167], v[170:171], v[238:239]
	v_pk_add_f32 v[168:169], v[168:169], v[236:237]
	v_pk_mul_f32 v[164:165], v[166:167], 0.5 op_sel_hi:[1, 0]
	v_pk_mul_f32 v[166:167], v[168:169], 0.5 op_sel_hi:[1, 0]
	v_add_u32_e32 v168, 0x890, v172
	v_ashrrev_i32_e32 v169, 31, v168
	v_lshlrev_b64 v[174:175], 2, v[168:169]
	v_lshl_add_u64 v[178:179], s[14:15], 0, v[174:175]
	v_lshl_add_u64 v[168:169], s[18:19], 0, v[174:175]
	v_mad_i64_i32 v[174:175], s[36:37], s49, v211, v[178:179]
	global_load_dwordx4 v[168:171], v[168:169], off
	global_load_dwordx4 v[174:177], v[174:175], off
	v_mad_i64_i32 v[212:213], s[36:37], s47, v211, v[178:179]
	global_load_dwordx4 v[212:215], v[212:213], off
	v_mad_i64_i32 v[216:217], s[36:37], s46, v211, v[178:179]
	global_load_dwordx4 v[216:219], v[216:217], off
	v_mad_i64_i32 v[220:221], s[36:37], s45, v211, v[178:179]
	global_load_dwordx4 v[220:223], v[220:221], off
	v_mad_i64_i32 v[224:225], s[36:37], s79, v211, v[178:179]
	global_load_dwordx4 v[224:227], v[224:225], off
	v_mad_i64_i32 v[228:229], s[36:37], s78, v211, v[178:179]
	global_load_dwordx4 v[228:231], v[228:229], off
	v_mad_i64_i32 v[232:233], s[36:37], s77, v211, v[178:179]
	global_load_dwordx4 v[232:235], v[232:233], off
	v_mad_i64_i32 v[236:237], s[36:37], s76, v211, v[178:179]
	global_load_dwordx4 v[236:239], v[236:237], off
	v_lshlrev_b64 v[172:173], 2, v[172:173]
	s_waitcnt vmcnt(7)
	v_pk_add_f32 v[174:175], v[168:169], v[174:175]
	v_pk_add_f32 v[176:177], v[170:171], v[176:177]
	s_waitcnt vmcnt(6)
	v_pk_add_f32 v[174:175], v[174:175], v[212:213]
	v_pk_add_f32 v[176:177], v[176:177], v[214:215]
	s_waitcnt vmcnt(5)
	v_pk_add_f32 v[174:175], v[174:175], v[216:217]
	v_pk_add_f32 v[176:177], v[176:177], v[218:219]
	s_waitcnt vmcnt(4)
	v_pk_add_f32 v[174:175], v[174:175], v[220:221]
	v_pk_add_f32 v[176:177], v[176:177], v[222:223]
	s_waitcnt vmcnt(3)
	v_pk_add_f32 v[174:175], v[174:175], v[224:225]
	v_pk_add_f32 v[176:177], v[176:177], v[226:227]
	s_waitcnt vmcnt(2)
	v_pk_add_f32 v[174:175], v[174:175], v[228:229]
	v_pk_add_f32 v[176:177], v[176:177], v[230:231]
	s_waitcnt vmcnt(1)
	v_pk_add_f32 v[174:175], v[174:175], v[232:233]
	v_pk_add_f32 v[176:177], v[176:177], v[234:235]
	v_add_u32_e32 v178, s75, v181
	v_ashrrev_i32_e32 v179, 31, v178
	s_waitcnt vmcnt(0)
	v_pk_add_f32 v[170:171], v[176:177], v[238:239]
	v_pk_add_f32 v[174:175], v[174:175], v[236:237]
	v_pk_mul_f32 v[168:169], v[170:171], 0.5 op_sel_hi:[1, 0]
	v_pk_mul_f32 v[170:171], v[174:175], 0.5 op_sel_hi:[1, 0]
	v_lshl_add_u64 v[174:175], s[12:13], 0, v[172:173]
	v_lshlrev_b64 v[176:177], 12, v[178:179]
	v_lshl_add_u64 v[204:205], v[174:175], 0, v[176:177]
	v_mbcnt_lo_u32_b32 v180, -1, 0
	v_mbcnt_hi_u32_b32 v180, -1, v180
	v_lshrrev_b32_e32 v180, 4, v180
	v_and_b32_e32 v181, 1, v180
	v_lshlrev_b32_e32 v181, 16, v181
	v_lshrrev_b32_e32 v184, 1, v180
	v_lshl_add_u32 v181, v184, 9, v181
	v_lshlrev_b32_e32 v180, 4, v180
	v_sub_u32_e32 v180, v181, v180
	v_mov_b32_e32 v181, 0
	v_lshl_add_u64 v[180:181], v[204:205], 0, v[180:181]
	v_mov_b32_e32 v186, 0x20000
	v_mov_b32_e32 v187, 0
	v_lshl_add_u64 v[184:185], v[180:181], 0, v[186:187]
	global_load_dword v182, v[184:185], off
	v_mov_b32_e32 v186, 0x60000
	v_lshl_add_u64 v[184:185], v[184:185], 0, v[186:187]
	global_load_dword v182, v[184:185], off
	v_mov_b32_e32 v186, 0x20000
	v_lshl_add_u64 v[184:185], v[184:185], 0, v[186:187]
	global_load_dword v182, v[184:185], off
	global_load_dwordx4 v[212:215], v[204:205], off
	global_load_dwordx4 v[216:219], v[204:205], off offset:64
	global_load_dwordx4 v[220:223], v[204:205], off offset:512
	global_load_dwordx4 v[224:227], v[204:205], off offset:576
	v_or_b32_e32 v204, 16, v178
	v_ashrrev_i32_e32 v205, 31, v204
	v_lshlrev_b64 v[204:205], 12, v[204:205]
	v_lshl_add_u64 v[206:207], v[174:175], 0, v[204:205]
	global_load_dwordx4 v[228:231], v[206:207], off
	global_load_dwordx4 v[232:235], v[206:207], off offset:64
	global_load_dwordx4 v[236:239], v[206:207], off offset:512
	global_load_dwordx4 v[240:243], v[206:207], off offset:576
	v_lshl_add_u64 v[206:207], s[12:13], 0, v[176:177]
	v_lshl_add_u64 v[206:207], v[206:207], 0, v[172:173]
	s_waitcnt vmcnt(7)
	v_pk_fma_f32 v[126:127], v[126:127], v[156:157], v[214:215]
	v_pk_fma_f32 v[124:125], v[124:125], v[158:159], v[212:213]
	s_waitcnt vmcnt(5)
	v_pk_fma_f32 v[110:111], v[110:111], v[164:165], v[222:223]
	v_pk_fma_f32 v[108:109], v[108:109], v[166:167], v[220:221]
	global_store_dwordx4 v[206:207], v[108:111], off offset:512
	s_waitcnt vmcnt(5)
	v_pk_fma_f32 v[106:107], v[106:107], v[168:169], v[226:227]
	v_pk_fma_f32 v[104:105], v[104:105], v[170:171], v[224:225]
	v_lshl_add_u64 v[108:109], s[12:13], 0, v[204:205]
	v_lshl_add_u64 v[108:109], v[108:109], 0, v[172:173]
	s_waitcnt vmcnt(1)
	v_pk_fma_f32 v[98:99], v[98:99], v[168:169], v[242:243]
	v_pk_fma_f32 v[96:97], v[96:97], v[170:171], v[240:241]
	global_store_dwordx4 v[108:109], v[96:99], off offset:576
	global_store_dwordx4 v[206:207], v[104:107], off offset:576
	v_pk_fma_f32 v[122:123], v[122:123], v[160:161], v[218:219]
	v_or_b32_e32 v96, 32, v178
	v_pk_fma_f32 v[106:107], v[118:119], v[156:157], v[230:231]
	v_pk_fma_f32 v[104:105], v[116:117], v[158:159], v[228:229]
	v_ashrrev_i32_e32 v97, 31, v96
	v_pk_fma_f32 v[120:121], v[120:121], v[162:163], v[216:217]
	global_store_dwordx4 v[108:109], v[104:107], off
	v_pk_fma_f32 v[102:103], v[102:103], v[164:165], v[238:239]
	v_pk_fma_f32 v[100:101], v[100:101], v[166:167], v[236:237]
	v_pk_fma_f32 v[106:107], v[114:115], v[160:161], v[234:235]
	v_pk_fma_f32 v[104:105], v[112:113], v[162:163], v[232:233]
	v_lshlrev_b64 v[204:205], 12, v[96:97]
	v_or_b32_e32 v112, 48, v178
	global_store_dwordx4 v[206:207], v[124:127], off
	global_store_dwordx4 v[206:207], v[120:123], off offset:64
	global_store_dwordx4 v[108:109], v[104:107], off offset:64
	global_store_dwordx4 v[108:109], v[100:103], off offset:512
	v_lshl_add_u64 v[108:109], v[174:175], 0, v[204:205]
	v_ashrrev_i32_e32 v113, 31, v112
	global_load_dwordx4 v[96:99], v[108:109], off
	global_load_dwordx4 v[100:103], v[108:109], off offset:64
	global_load_dwordx4 v[104:107], v[108:109], off offset:512
	s_nop 0
	global_load_dwordx4 v[108:111], v[108:109], off offset:576
	v_lshlrev_b64 v[178:179], 12, v[112:113]
	v_lshl_add_u64 v[124:125], v[174:175], 0, v[178:179]
	global_load_dwordx4 v[112:115], v[124:125], off
	global_load_dwordx4 v[116:119], v[124:125], off offset:64
	global_load_dwordx4 v[120:123], v[124:125], off offset:512
	s_nop 0
	global_load_dwordx4 v[124:127], v[124:125], off offset:576
	s_waitcnt vmcnt(7)
	v_pk_fma_f32 v[92:93], v[92:93], v[158:159], v[96:97]
	v_lshl_add_u64 v[96:97], s[12:13], 0, v[204:205]
	v_lshl_add_u64 v[96:97], v[96:97], 0, v[172:173]
	s_waitcnt vmcnt(5)
	v_pk_fma_f32 v[78:79], v[78:79], v[164:165], v[106:107]
	v_pk_fma_f32 v[76:77], v[76:77], v[166:167], v[104:105]
	global_store_dwordx4 v[96:97], v[76:79], off offset:512
	s_waitcnt vmcnt(5)
	v_pk_fma_f32 v[74:75], v[74:75], v[168:169], v[110:111]
	v_pk_fma_f32 v[72:73], v[72:73], v[170:171], v[108:109]
	v_lshl_add_u64 v[76:77], s[12:13], 0, v[178:179]
	v_pk_fma_f32 v[94:95], v[94:95], v[156:157], v[98:99]
	v_pk_fma_f32 v[90:91], v[90:91], v[160:161], v[102:103]
	v_pk_fma_f32 v[88:89], v[88:89], v[162:163], v[100:101]
	global_store_dwordx4 v[96:97], v[72:75], off offset:576
	v_lshl_add_u64 v[76:77], v[76:77], 0, v[172:173]
	global_store_dwordx4 v[96:97], v[92:95], off
	s_waitcnt vmcnt(6)
	v_pk_fma_f32 v[74:75], v[86:87], v[156:157], v[114:115]
	v_pk_fma_f32 v[72:73], v[84:85], v[158:159], v[112:113]
	global_store_dwordx4 v[96:97], v[88:91], off offset:64
	global_store_dwordx4 v[76:77], v[72:75], off
	s_waitcnt vmcnt(6)
	v_pk_fma_f32 v[70:71], v[70:71], v[164:165], v[122:123]
	v_pk_fma_f32 v[68:69], v[68:69], v[166:167], v[120:121]
	v_pk_fma_f32 v[74:75], v[82:83], v[160:161], v[118:119]
	v_pk_fma_f32 v[72:73], v[80:81], v[162:163], v[116:117]
	s_waitcnt vmcnt(5)
	v_pk_fma_f32 v[66:67], v[66:67], v[168:169], v[126:127]
	v_pk_fma_f32 v[64:65], v[64:65], v[170:171], v[124:125]
	v_lshl_add_u64 v[96:97], v[176:177], 0, s[20:21]
	global_store_dwordx4 v[76:77], v[72:75], off offset:64
	global_store_dwordx4 v[76:77], v[68:71], off offset:512
	global_store_dwordx4 v[76:77], v[64:67], off offset:576
	v_lshl_add_u64 v[76:77], v[174:175], 0, v[96:97]
	global_load_dwordx4 v[64:67], v[76:77], off
	global_load_dwordx4 v[68:71], v[76:77], off offset:64
	global_load_dwordx4 v[72:75], v[76:77], off offset:512
	s_nop 0
	global_load_dwordx4 v[76:79], v[76:77], off offset:576
	v_lshl_add_u64 v[98:99], v[176:177], 0, s[22:23]
	v_lshl_add_u64 v[92:93], v[174:175], 0, v[98:99]
	global_load_dwordx4 v[80:83], v[92:93], off
	global_load_dwordx4 v[84:87], v[92:93], off offset:64
	global_load_dwordx4 v[88:91], v[92:93], off offset:512
	s_nop 0
	global_load_dwordx4 v[92:95], v[92:93], off offset:576
	s_waitcnt vmcnt(7)
	v_pk_fma_f32 v[60:61], v[60:61], v[158:159], v[64:65]
	v_lshl_add_u64 v[64:65], s[12:13], 0, v[96:97]
	v_lshl_add_u64 v[64:65], v[64:65], 0, v[172:173]
	s_waitcnt vmcnt(5)
	v_pk_fma_f32 v[46:47], v[46:47], v[164:165], v[74:75]
	v_pk_fma_f32 v[44:45], v[44:45], v[166:167], v[72:73]
	global_store_dwordx4 v[64:65], v[44:47], off offset:512
	s_waitcnt vmcnt(5)
	v_pk_fma_f32 v[42:43], v[42:43], v[168:169], v[78:79]
	v_pk_fma_f32 v[40:41], v[40:41], v[170:171], v[76:77]
	v_lshl_add_u64 v[44:45], s[12:13], 0, v[98:99]
	v_pk_fma_f32 v[62:63], v[62:63], v[156:157], v[66:67]
	v_pk_fma_f32 v[58:59], v[58:59], v[160:161], v[70:71]
	v_pk_fma_f32 v[56:57], v[56:57], v[162:163], v[68:69]
	global_store_dwordx4 v[64:65], v[40:43], off offset:576
	v_lshl_add_u64 v[44:45], v[44:45], 0, v[172:173]
	global_store_dwordx4 v[64:65], v[60:63], off
	s_waitcnt vmcnt(6)
	v_pk_fma_f32 v[42:43], v[54:55], v[156:157], v[82:83]
	v_pk_fma_f32 v[40:41], v[52:53], v[158:159], v[80:81]
	global_store_dwordx4 v[64:65], v[56:59], off offset:64
	global_store_dwordx4 v[44:45], v[40:43], off
	s_waitcnt vmcnt(6)
	v_pk_fma_f32 v[38:39], v[38:39], v[164:165], v[90:91]
	v_pk_fma_f32 v[36:37], v[36:37], v[166:167], v[88:89]
	v_pk_fma_f32 v[42:43], v[50:51], v[160:161], v[86:87]
	v_pk_fma_f32 v[40:41], v[48:49], v[162:163], v[84:85]
	s_waitcnt vmcnt(5)
	v_pk_fma_f32 v[34:35], v[34:35], v[168:169], v[94:95]
	v_pk_fma_f32 v[32:33], v[32:33], v[170:171], v[92:93]
	v_lshl_add_u64 v[64:65], v[176:177], 0, s[24:25]
	global_store_dwordx4 v[44:45], v[40:43], off offset:64
	global_store_dwordx4 v[44:45], v[36:39], off offset:512
	global_store_dwordx4 v[44:45], v[32:35], off offset:576
	v_lshl_add_u64 v[44:45], v[174:175], 0, v[64:65]
	global_load_dwordx4 v[32:35], v[44:45], off
	global_load_dwordx4 v[36:39], v[44:45], off offset:64
	global_load_dwordx4 v[40:43], v[44:45], off offset:512
	s_nop 0
	global_load_dwordx4 v[44:47], v[44:45], off offset:576
	v_lshl_add_u64 v[66:67], v[176:177], 0, s[26:27]
	v_lshl_add_u64 v[60:61], v[174:175], 0, v[66:67]
	global_load_dwordx4 v[48:51], v[60:61], off
	global_load_dwordx4 v[52:55], v[60:61], off offset:64
	global_load_dwordx4 v[56:59], v[60:61], off offset:512
	s_nop 0
	global_load_dwordx4 v[60:63], v[60:61], off offset:576
	s_waitcnt vmcnt(7)
	v_pk_fma_f32 v[28:29], v[28:29], v[158:159], v[32:33]
	v_lshl_add_u64 v[32:33], s[12:13], 0, v[64:65]
	v_lshl_add_u64 v[32:33], v[32:33], 0, v[172:173]
	s_waitcnt vmcnt(5)
	v_pk_fma_f32 v[18:19], v[18:19], v[164:165], v[42:43]
	v_pk_fma_f32 v[16:17], v[16:17], v[166:167], v[40:41]
	global_store_dwordx4 v[32:33], v[16:19], off offset:512
	s_waitcnt vmcnt(5)
	v_pk_fma_f32 v[10:11], v[10:11], v[168:169], v[46:47]
	v_pk_fma_f32 v[8:9], v[8:9], v[170:171], v[44:45]
	v_lshl_add_u64 v[16:17], s[12:13], 0, v[66:67]
	global_store_dwordx4 v[32:33], v[8:11], off offset:576
	v_lshl_add_u64 v[16:17], v[16:17], 0, v[172:173]
	v_pk_fma_f32 v[30:31], v[30:31], v[156:157], v[34:35]
	s_waitcnt vmcnt(5)
	v_pk_fma_f32 v[10:11], v[22:23], v[156:157], v[50:51]
	v_pk_fma_f32 v[8:9], v[20:21], v[158:159], v[48:49]
	v_pk_fma_f32 v[26:27], v[26:27], v[160:161], v[38:39]
	v_pk_fma_f32 v[24:25], v[24:25], v[162:163], v[36:37]
	global_store_dwordx4 v[16:17], v[8:11], off
	s_waitcnt vmcnt(4)
	v_pk_fma_f32 v[6:7], v[6:7], v[164:165], v[58:59]
	v_pk_fma_f32 v[4:5], v[4:5], v[166:167], v[56:57]
	v_pk_fma_f32 v[10:11], v[14:15], v[160:161], v[54:55]
	v_pk_fma_f32 v[8:9], v[12:13], v[162:163], v[52:53]
	s_waitcnt vmcnt(3)
	v_pk_fma_f32 v[2:3], v[2:3], v[168:169], v[62:63]
	v_pk_fma_f32 v[0:1], v[0:1], v[170:171], v[60:61]
	global_store_dwordx4 v[32:33], v[28:31], off
	global_store_dwordx4 v[32:33], v[24:27], off offset:64
	global_store_dwordx4 v[16:17], v[8:11], off offset:64
	global_store_dwordx4 v[16:17], v[4:7], off offset:512
	global_store_dwordx4 v[16:17], v[0:3], off offset:576
	s_waitcnt vmcnt(0)
	s_barrier
	s_and_saveexec_b64 s[36:37], s[4:5]
	s_cbranch_execz .LBB0_1662
	s_lshl_b32 s38, s44, 2
	s_ashr_i32 s39, s38, 31
	s_lshl_b64 s[38:39], s[38:39], 2
	s_add_u32 s38, s63, s38
	s_addc_u32 s39, s64, s39
	s_getreg_b32 s40, hwreg(HW_REG_XCC_ID, 0, 4)
	global_load_dwordx4 v[0:3], v129, s[38:39]
	s_and_b32 s38, s40, 15
	s_add_i32 s38, s38, 1
	s_waitcnt vmcnt(0)
	v_cmp_ne_u32_e32 vcc, s38, v2
	s_nop 1
	v_cndmask_b32_e64 v2, 0, 1, vcc
	v_cmp_ne_u32_e32 vcc, s38, v3
	v_lshlrev_b32_e32 v2, 2, v2
	s_nop 0
	v_cndmask_b32_e64 v3, 0, 1, vcc
	v_cmp_ne_u32_e32 vcc, s38, v1
	v_lshlrev_b32_e32 v3, 3, v3
	v_or_b32_e32 v2, v3, v2
	v_cndmask_b32_e64 v1, 0, 1, vcc
	v_cmp_ne_u32_e32 vcc, s38, v0
	v_lshlrev_b32_e32 v1, 1, v1
	s_nop 0
	v_cndmask_b32_e64 v0, 0, 1, vcc
	v_or_b32_e32 v0, v0, v1
	v_and_b32_e32 v0, 3, v0
	v_or_b32_e32 v0, v0, v2
	v_and_b32_e32 v0, 15, v0
	v_cmp_eq_u32_e32 vcc, 0, v0
	s_cbranch_vccnz .LBB0_1651
	buffer_wbl2 sc1
	s_waitcnt vmcnt(0)

.LBB0_2361:
	v_lshl_or_b32 v172, s42, 8, v198
	v_add_u32_e32 v156, 0x1400, v172
	v_ashrrev_i32_e32 v157, 31, v156
	s_ashr_i32 s55, s44, 3
	v_lshlrev_b64 v[160:161], 2, v[156:157]
	s_add_i32 s56, s55, 64
	v_lshl_add_u64 v[164:165], s[2:3], 0, v[160:161]
	v_lshl_add_u64 v[156:157], s[18:19], 0, v[160:161]
	v_mad_i64_i32 v[160:161], s[46:47], s56, v211, v[164:165]
	global_load_dwordx4 v[156:159], v[156:157], off
	s_add_i32 s54, s55, 0x48
	s_add_i32 s53, s55, 0x50
	s_add_i32 s52, s55, 0x58
	s_add_i32 s81, s55, 0x60
	s_add_i32 s80, s55, 0x68
	s_add_i32 s43, s55, 0x70
	s_add_i32 s37, s55, 0x78
	s_lshl_b32 s35, s44, 8
	global_load_dwordx4 v[160:163], v[160:161], off
	v_mad_i64_i32 v[212:213], s[46:47], s54, v211, v[164:165]
	global_load_dwordx4 v[212:215], v[212:213], off
	v_mad_i64_i32 v[216:217], s[46:47], s53, v211, v[164:165]
	global_load_dwordx4 v[216:219], v[216:217], off
	v_mad_i64_i32 v[220:221], s[46:47], s52, v211, v[164:165]
	global_load_dwordx4 v[220:223], v[220:221], off
	v_mad_i64_i32 v[224:225], s[46:47], s81, v211, v[164:165]
	global_load_dwordx4 v[224:227], v[224:225], off
	v_mad_i64_i32 v[228:229], s[46:47], s80, v211, v[164:165]
	global_load_dwordx4 v[228:231], v[228:229], off
	v_mad_i64_i32 v[232:233], s[46:47], s43, v211, v[164:165]
	global_load_dwordx4 v[232:235], v[232:233], off
	v_mad_i64_i32 v[236:237], s[46:47], s37, v211, v[164:165]
	global_load_dwordx4 v[236:239], v[236:237], off
	v_ashrrev_i32_e32 v173, 31, v172
	v_readfirstlane_b32 s82, v180
	s_waitcnt vmcnt(7)
	v_pk_add_f32 v[160:161], v[156:157], v[160:161]
	v_pk_add_f32 v[162:163], v[158:159], v[162:163]
	s_waitcnt vmcnt(6)
	v_pk_add_f32 v[160:161], v[160:161], v[212:213]
	v_pk_add_f32 v[162:163], v[162:163], v[214:215]
	s_waitcnt vmcnt(5)
	v_pk_add_f32 v[160:161], v[160:161], v[216:217]
	v_pk_add_f32 v[162:163], v[162:163], v[218:219]
	s_waitcnt vmcnt(4)
	v_pk_add_f32 v[160:161], v[160:161], v[220:221]
	v_pk_add_f32 v[162:163], v[162:163], v[222:223]
	s_waitcnt vmcnt(3)
	v_pk_add_f32 v[160:161], v[160:161], v[224:225]
	v_pk_add_f32 v[162:163], v[162:163], v[226:227]
	s_waitcnt vmcnt(2)
	v_pk_add_f32 v[160:161], v[160:161], v[228:229]
	v_pk_add_f32 v[162:163], v[162:163], v[230:231]
	s_waitcnt vmcnt(1)
	v_pk_add_f32 v[166:167], v[160:161], v[232:233]
	v_pk_add_f32 v[162:163], v[162:163], v[234:235]
	s_waitcnt vmcnt(0)
	v_pk_add_f32 v[156:157], v[162:163], v[238:239]
	v_add_u32_e32 v160, 0x1410, v172
	v_ashrrev_i32_e32 v161, 31, v160
	v_lshlrev_b64 v[164:165], 2, v[160:161]
	v_lshl_add_u64 v[168:169], s[2:3], 0, v[164:165]
	v_lshl_add_u64 v[160:161], s[18:19], 0, v[164:165]
	v_mad_i64_i32 v[164:165], s[46:47], s56, v211, v[168:169]
	v_pk_add_f32 v[158:159], v[166:167], v[236:237]
	global_load_dwordx4 v[160:163], v[160:161], off
	global_load_dwordx4 v[164:167], v[164:165], off
	v_mad_i64_i32 v[212:213], s[46:47], s54, v211, v[168:169]
	global_load_dwordx4 v[212:215], v[212:213], off
	v_mad_i64_i32 v[216:217], s[46:47], s53, v211, v[168:169]
	global_load_dwordx4 v[216:219], v[216:217], off
	v_mad_i64_i32 v[220:221], s[46:47], s52, v211, v[168:169]
	global_load_dwordx4 v[220:223], v[220:221], off
	v_mad_i64_i32 v[224:225], s[46:47], s81, v211, v[168:169]
	global_load_dwordx4 v[224:227], v[224:225], off
	v_mad_i64_i32 v[228:229], s[46:47], s80, v211, v[168:169]
	global_load_dwordx4 v[228:231], v[228:229], off
	v_mad_i64_i32 v[232:233], s[46:47], s43, v211, v[168:169]
	global_load_dwordx4 v[232:235], v[232:233], off
	v_mad_i64_i32 v[236:237], s[46:47], s37, v211, v[168:169]
	global_load_dwordx4 v[236:239], v[236:237], off
	s_waitcnt vmcnt(7)
	v_pk_add_f32 v[164:165], v[160:161], v[164:165]
	v_pk_add_f32 v[166:167], v[162:163], v[166:167]
	s_waitcnt vmcnt(6)
	v_pk_add_f32 v[164:165], v[164:165], v[212:213]
	v_pk_add_f32 v[166:167], v[166:167], v[214:215]
	s_waitcnt vmcnt(5)
	v_pk_add_f32 v[164:165], v[164:165], v[216:217]
	v_pk_add_f32 v[166:167], v[166:167], v[218:219]
	s_waitcnt vmcnt(4)
	v_pk_add_f32 v[164:165], v[164:165], v[220:221]
	v_pk_add_f32 v[166:167], v[166:167], v[222:223]
	s_waitcnt vmcnt(3)
	v_pk_add_f32 v[164:165], v[164:165], v[224:225]
	v_pk_add_f32 v[166:167], v[166:167], v[226:227]
	s_waitcnt vmcnt(2)
	v_pk_add_f32 v[164:165], v[164:165], v[228:229]
	v_pk_add_f32 v[166:167], v[166:167], v[230:231]
	s_waitcnt vmcnt(1)
	v_pk_add_f32 v[170:171], v[164:165], v[232:233]
	v_pk_add_f32 v[166:167], v[166:167], v[234:235]
	s_waitcnt vmcnt(0)
	v_pk_add_f32 v[160:161], v[166:167], v[238:239]
	v_add_u32_e32 v164, 0x1480, v172
	v_ashrrev_i32_e32 v165, 31, v164
	v_lshlrev_b64 v[168:169], 2, v[164:165]
	v_lshl_add_u64 v[174:175], s[2:3], 0, v[168:169]
	v_lshl_add_u64 v[164:165], s[18:19], 0, v[168:169]
	v_mad_i64_i32 v[168:169], s[46:47], s56, v211, v[174:175]
	v_pk_add_f32 v[162:163], v[170:171], v[236:237]
	global_load_dwordx4 v[164:167], v[164:165], off
	global_load_dwordx4 v[168:171], v[168:169], off
	v_mad_i64_i32 v[212:213], s[46:47], s54, v211, v[174:175]
	global_load_dwordx4 v[212:215], v[212:213], off
	v_mad_i64_i32 v[216:217], s[46:47], s53, v211, v[174:175]
	global_load_dwordx4 v[216:219], v[216:217], off
	v_mad_i64_i32 v[220:221], s[46:47], s52, v211, v[174:175]
	global_load_dwordx4 v[220:223], v[220:221], off
	v_mad_i64_i32 v[224:225], s[46:47], s81, v211, v[174:175]
	global_load_dwordx4 v[224:227], v[224:225], off
	v_mad_i64_i32 v[228:229], s[46:47], s80, v211, v[174:175]
	global_load_dwordx4 v[228:231], v[228:229], off
	v_mad_i64_i32 v[232:233], s[46:47], s43, v211, v[174:175]
	global_load_dwordx4 v[232:235], v[232:233], off
	v_mad_i64_i32 v[236:237], s[46:47], s37, v211, v[174:175]
	global_load_dwordx4 v[236:239], v[236:237], off
	s_waitcnt vmcnt(7)
	v_pk_add_f32 v[168:169], v[164:165], v[168:169]
	v_pk_add_f32 v[170:171], v[166:167], v[170:171]
	s_waitcnt vmcnt(6)
	v_pk_add_f32 v[168:169], v[168:169], v[212:213]
	v_pk_add_f32 v[170:171], v[170:171], v[214:215]
	s_waitcnt vmcnt(5)
	v_pk_add_f32 v[168:169], v[168:169], v[216:217]
	v_pk_add_f32 v[170:171], v[170:171], v[218:219]
	s_waitcnt vmcnt(4)
	v_pk_add_f32 v[168:169], v[168:169], v[220:221]
	v_pk_add_f32 v[170:171], v[170:171], v[222:223]
	s_waitcnt vmcnt(3)
	v_pk_add_f32 v[168:169], v[168:169], v[224:225]
	v_pk_add_f32 v[170:171], v[170:171], v[226:227]
	s_waitcnt vmcnt(2)
	v_pk_add_f32 v[168:169], v[168:169], v[228:229]
	v_pk_add_f32 v[170:171], v[170:171], v[230:231]
	s_waitcnt vmcnt(1)
	v_pk_add_f32 v[176:177], v[168:169], v[232:233]
	v_pk_add_f32 v[170:171], v[170:171], v[234:235]
	s_waitcnt vmcnt(0)
	v_pk_add_f32 v[164:165], v[170:171], v[238:239]
	v_add_u32_e32 v168, 0x1490, v172
	v_ashrrev_i32_e32 v169, 31, v168
	v_lshlrev_b64 v[174:175], 2, v[168:169]
	v_lshl_add_u64 v[178:179], s[2:3], 0, v[174:175]
	v_lshl_add_u64 v[168:169], s[18:19], 0, v[174:175]
	v_mad_i64_i32 v[174:175], s[46:47], s56, v211, v[178:179]
	v_pk_add_f32 v[166:167], v[176:177], v[236:237]
	global_load_dwordx4 v[168:171], v[168:169], off
	global_load_dwordx4 v[174:177], v[174:175], off
	v_mad_i64_i32 v[212:213], s[46:47], s54, v211, v[178:179]
	global_load_dwordx4 v[212:215], v[212:213], off
	v_mad_i64_i32 v[216:217], s[46:47], s53, v211, v[178:179]
	global_load_dwordx4 v[216:219], v[216:217], off
	v_mad_i64_i32 v[220:221], s[46:47], s52, v211, v[178:179]
	global_load_dwordx4 v[220:223], v[220:221], off
	v_mad_i64_i32 v[224:225], s[46:47], s81, v211, v[178:179]
	global_load_dwordx4 v[224:227], v[224:225], off
	v_mad_i64_i32 v[228:229], s[46:47], s80, v211, v[178:179]
	global_load_dwordx4 v[228:231], v[228:229], off
	v_mad_i64_i32 v[232:233], s[46:47], s43, v211, v[178:179]
	global_load_dwordx4 v[232:235], v[232:233], off
	v_mad_i64_i32 v[236:237], s[46:47], s37, v211, v[178:179]
	global_load_dwordx4 v[236:239], v[236:237], off
	v_lshlrev_b64 v[172:173], 2, v[172:173]
	s_waitcnt vmcnt(7)
	v_pk_add_f32 v[174:175], v[168:169], v[174:175]
	v_pk_add_f32 v[176:177], v[170:171], v[176:177]
	s_waitcnt vmcnt(6)
	v_pk_add_f32 v[174:175], v[174:175], v[212:213]
	v_pk_add_f32 v[176:177], v[176:177], v[214:215]
	s_waitcnt vmcnt(5)
	v_pk_add_f32 v[174:175], v[174:175], v[216:217]
	v_pk_add_f32 v[176:177], v[176:177], v[218:219]
	s_waitcnt vmcnt(4)
	v_pk_add_f32 v[174:175], v[174:175], v[220:221]
	v_pk_add_f32 v[176:177], v[176:177], v[222:223]
	s_waitcnt vmcnt(3)
	v_pk_add_f32 v[174:175], v[174:175], v[224:225]
	v_pk_add_f32 v[176:177], v[176:177], v[226:227]
	s_waitcnt vmcnt(2)
	v_pk_add_f32 v[174:175], v[174:175], v[228:229]
	v_pk_add_f32 v[176:177], v[176:177], v[230:231]
	s_waitcnt vmcnt(1)
	v_pk_add_f32 v[204:205], v[174:175], v[232:233]
	v_pk_add_f32 v[170:171], v[176:177], v[234:235]
	v_add_u32_e32 v178, s35, v181
	v_ashrrev_i32_e32 v179, 31, v178
	s_waitcnt vmcnt(0)
	v_pk_add_f32 v[168:169], v[170:171], v[238:239]
	v_pk_add_f32 v[170:171], v[204:205], v[236:237]
	v_lshl_add_u64 v[174:175], s[0:1], 0, v[172:173]
	v_lshlrev_b64 v[176:177], 12, v[178:179]
	v_lshl_add_u64 v[204:205], v[174:175], 0, v[176:177]
	v_mbcnt_lo_u32_b32 v180, -1, 0
	v_mbcnt_hi_u32_b32 v180, -1, v180
	v_lshrrev_b32_e32 v180, 4, v180
	v_and_b32_e32 v181, 1, v180
	v_lshlrev_b32_e32 v181, 16, v181
	v_lshrrev_b32_e32 v184, 1, v180
	v_lshl_add_u32 v181, v184, 9, v181
	v_lshlrev_b32_e32 v180, 4, v180
	v_sub_u32_e32 v180, v181, v180
	v_mov_b32_e32 v181, 0
	v_lshl_add_u64 v[180:181], v[204:205], 0, v[180:181]
	v_mov_b32_e32 v186, 0x20000
	v_mov_b32_e32 v187, 0
	v_lshl_add_u64 v[184:185], v[180:181], 0, v[186:187]
	global_load_dword v182, v[184:185], off
	v_mov_b32_e32 v186, 0x60000
	v_lshl_add_u64 v[184:185], v[184:185], 0, v[186:187]
	global_load_dword v182, v[184:185], off
	v_mov_b32_e32 v186, 0x20000
	v_lshl_add_u64 v[184:185], v[184:185], 0, v[186:187]
	global_load_dword v182, v[184:185], off
	global_load_dwordx4 v[212:215], v[204:205], off
	global_load_dwordx4 v[216:219], v[204:205], off offset:64
	global_load_dwordx4 v[220:223], v[204:205], off offset:512
	global_load_dwordx4 v[224:227], v[204:205], off offset:576
	v_or_b32_e32 v204, 16, v178
	v_ashrrev_i32_e32 v205, 31, v204
	v_lshlrev_b64 v[204:205], 12, v[204:205]
	v_lshl_add_u64 v[206:207], v[174:175], 0, v[204:205]
	global_load_dwordx4 v[228:231], v[206:207], off
	global_load_dwordx4 v[232:235], v[206:207], off offset:64
	global_load_dwordx4 v[236:239], v[206:207], off offset:512
	global_load_dwordx4 v[240:243], v[206:207], off offset:576
	v_lshl_add_u64 v[206:207], s[0:1], 0, v[176:177]
	v_lshl_add_u64 v[206:207], v[206:207], 0, v[172:173]
	s_waitcnt vmcnt(7)
	v_pk_fma_f32 v[126:127], v[126:127], v[156:157], v[214:215]
	v_pk_fma_f32 v[124:125], v[124:125], v[158:159], v[212:213]
	s_waitcnt vmcnt(5)
	v_pk_fma_f32 v[110:111], v[110:111], v[164:165], v[222:223]
	v_pk_fma_f32 v[108:109], v[108:109], v[166:167], v[220:221]
	global_store_dwordx4 v[206:207], v[108:111], off offset:512
	s_waitcnt vmcnt(5)
	v_pk_fma_f32 v[106:107], v[106:107], v[168:169], v[226:227]
	v_pk_fma_f32 v[104:105], v[104:105], v[170:171], v[224:225]
	v_lshl_add_u64 v[108:109], s[0:1], 0, v[204:205]
	v_lshl_add_u64 v[108:109], v[108:109], 0, v[172:173]
	s_waitcnt vmcnt(1)
	v_pk_fma_f32 v[98:99], v[98:99], v[168:169], v[242:243]
	v_pk_fma_f32 v[96:97], v[96:97], v[170:171], v[240:241]
	global_store_dwordx4 v[108:109], v[96:99], off offset:576
	global_store_dwordx4 v[206:207], v[104:107], off offset:576
	v_pk_fma_f32 v[122:123], v[122:123], v[160:161], v[218:219]
	v_or_b32_e32 v96, 32, v178
	v_pk_fma_f32 v[106:107], v[118:119], v[156:157], v[230:231]
	v_pk_fma_f32 v[104:105], v[116:117], v[158:159], v[228:229]
	v_ashrrev_i32_e32 v97, 31, v96
	v_pk_fma_f32 v[120:121], v[120:121], v[162:163], v[216:217]
	global_store_dwordx4 v[108:109], v[104:107], off
	v_pk_fma_f32 v[102:103], v[102:103], v[164:165], v[238:239]
	v_pk_fma_f32 v[100:101], v[100:101], v[166:167], v[236:237]
	v_pk_fma_f32 v[106:107], v[114:115], v[160:161], v[234:235]
	v_pk_fma_f32 v[104:105], v[112:113], v[162:163], v[232:233]
	v_lshlrev_b64 v[204:205], 12, v[96:97]
	v_or_b32_e32 v112, 48, v178
	global_store_dwordx4 v[206:207], v[124:127], off
	global_store_dwordx4 v[206:207], v[120:123], off offset:64
	global_store_dwordx4 v[108:109], v[104:107], off offset:64
	global_store_dwordx4 v[108:109], v[100:103], off offset:512
	v_lshl_add_u64 v[108:109], v[174:175], 0, v[204:205]
	v_ashrrev_i32_e32 v113, 31, v112
	global_load_dwordx4 v[96:99], v[108:109], off
	global_load_dwordx4 v[100:103], v[108:109], off offset:64
	global_load_dwordx4 v[104:107], v[108:109], off offset:512
	s_nop 0
	global_load_dwordx4 v[108:111], v[108:109], off offset:576
	v_lshlrev_b64 v[178:179], 12, v[112:113]
	v_lshl_add_u64 v[124:125], v[174:175], 0, v[178:179]
	global_load_dwordx4 v[112:115], v[124:125], off
	global_load_dwordx4 v[116:119], v[124:125], off offset:64
	global_load_dwordx4 v[120:123], v[124:125], off offset:512
	s_nop 0
	global_load_dwordx4 v[124:127], v[124:125], off offset:576
	s_waitcnt vmcnt(7)
	v_pk_fma_f32 v[92:93], v[92:93], v[158:159], v[96:97]
	v_lshl_add_u64 v[96:97], s[0:1], 0, v[204:205]
	v_lshl_add_u64 v[96:97], v[96:97], 0, v[172:173]
	s_waitcnt vmcnt(5)
	v_pk_fma_f32 v[78:79], v[78:79], v[164:165], v[106:107]
	v_pk_fma_f32 v[76:77], v[76:77], v[166:167], v[104:105]
	global_store_dwordx4 v[96:97], v[76:79], off offset:512
	s_waitcnt vmcnt(5)
	v_pk_fma_f32 v[74:75], v[74:75], v[168:169], v[110:111]
	v_pk_fma_f32 v[72:73], v[72:73], v[170:171], v[108:109]
	v_lshl_add_u64 v[76:77], s[0:1], 0, v[178:179]
	v_pk_fma_f32 v[94:95], v[94:95], v[156:157], v[98:99]
	v_pk_fma_f32 v[90:91], v[90:91], v[160:161], v[102:103]
	v_pk_fma_f32 v[88:89], v[88:89], v[162:163], v[100:101]
	global_store_dwordx4 v[96:97], v[72:75], off offset:576
	v_lshl_add_u64 v[76:77], v[76:77], 0, v[172:173]
	global_store_dwordx4 v[96:97], v[92:95], off
	s_waitcnt vmcnt(6)
	v_pk_fma_f32 v[74:75], v[86:87], v[156:157], v[114:115]
	v_pk_fma_f32 v[72:73], v[84:85], v[158:159], v[112:113]
	global_store_dwordx4 v[96:97], v[88:91], off offset:64
	global_store_dwordx4 v[76:77], v[72:75], off
	s_waitcnt vmcnt(6)
	v_pk_fma_f32 v[70:71], v[70:71], v[164:165], v[122:123]
	v_pk_fma_f32 v[68:69], v[68:69], v[166:167], v[120:121]
	v_pk_fma_f32 v[74:75], v[82:83], v[160:161], v[118:119]
	v_pk_fma_f32 v[72:73], v[80:81], v[162:163], v[116:117]
	s_waitcnt vmcnt(5)
	v_pk_fma_f32 v[66:67], v[66:67], v[168:169], v[126:127]
	v_pk_fma_f32 v[64:65], v[64:65], v[170:171], v[124:125]
	v_lshl_add_u64 v[96:97], v[176:177], 0, s[20:21]
	global_store_dwordx4 v[76:77], v[72:75], off offset:64
	global_store_dwordx4 v[76:77], v[68:71], off offset:512
	global_store_dwordx4 v[76:77], v[64:67], off offset:576
	v_lshl_add_u64 v[76:77], v[174:175], 0, v[96:97]
	global_load_dwordx4 v[64:67], v[76:77], off
	global_load_dwordx4 v[68:71], v[76:77], off offset:64
	global_load_dwordx4 v[72:75], v[76:77], off offset:512
	s_nop 0
	global_load_dwordx4 v[76:79], v[76:77], off offset:576
	v_lshl_add_u64 v[98:99], v[176:177], 0, s[22:23]
	v_lshl_add_u64 v[92:93], v[174:175], 0, v[98:99]
	global_load_dwordx4 v[80:83], v[92:93], off
	global_load_dwordx4 v[84:87], v[92:93], off offset:64
	global_load_dwordx4 v[88:91], v[92:93], off offset:512
	s_nop 0
	global_load_dwordx4 v[92:95], v[92:93], off offset:576
	s_waitcnt vmcnt(7)
	v_pk_fma_f32 v[60:61], v[60:61], v[158:159], v[64:65]
	v_lshl_add_u64 v[64:65], s[0:1], 0, v[96:97]
	v_lshl_add_u64 v[64:65], v[64:65], 0, v[172:173]
	s_waitcnt vmcnt(5)
	v_pk_fma_f32 v[46:47], v[46:47], v[164:165], v[74:75]
	v_pk_fma_f32 v[44:45], v[44:45], v[166:167], v[72:73]
	global_store_dwordx4 v[64:65], v[44:47], off offset:512
	s_waitcnt vmcnt(5)
	v_pk_fma_f32 v[42:43], v[42:43], v[168:169], v[78:79]
	v_pk_fma_f32 v[40:41], v[40:41], v[170:171], v[76:77]
	v_lshl_add_u64 v[44:45], s[0:1], 0, v[98:99]
	global_store_dwordx4 v[64:65], v[40:43], off offset:576
	v_lshl_add_u64 v[44:45], v[44:45], 0, v[172:173]
	v_pk_fma_f32 v[62:63], v[62:63], v[156:157], v[66:67]
	s_waitcnt vmcnt(5)
	v_pk_fma_f32 v[42:43], v[54:55], v[156:157], v[82:83]
	v_pk_fma_f32 v[40:41], v[52:53], v[158:159], v[80:81]
	v_pk_fma_f32 v[58:59], v[58:59], v[160:161], v[70:71]
	v_pk_fma_f32 v[56:57], v[56:57], v[162:163], v[68:69]
	global_store_dwordx4 v[44:45], v[40:43], off
	s_waitcnt vmcnt(4)
	v_pk_fma_f32 v[38:39], v[38:39], v[164:165], v[90:91]
	v_pk_fma_f32 v[36:37], v[36:37], v[166:167], v[88:89]
	v_pk_fma_f32 v[42:43], v[50:51], v[160:161], v[86:87]
	v_pk_fma_f32 v[40:41], v[48:49], v[162:163], v[84:85]
	s_waitcnt vmcnt(3)
	v_pk_fma_f32 v[34:35], v[34:35], v[168:169], v[94:95]
	v_pk_fma_f32 v[32:33], v[32:33], v[170:171], v[92:93]
	v_lshl_add_u64 v[66:67], v[176:177], 0, s[24:25]
	global_store_dwordx4 v[64:65], v[60:63], off
	global_store_dwordx4 v[64:65], v[56:59], off offset:64
	global_store_dwordx4 v[44:45], v[40:43], off offset:64
	global_store_dwordx4 v[44:45], v[36:39], off offset:512
	global_store_dwordx4 v[44:45], v[32:35], off offset:576
	v_lshl_add_u64 v[64:65], v[176:177], 0, s[26:27]
	v_lshl_add_u64 v[36:37], v[174:175], 0, v[64:65]
	v_lshl_add_u64 v[32:33], v[174:175], 0, v[66:67]
	global_load_dwordx4 v[48:51], v[32:33], off
	global_load_dwordx4 v[60:63], v[32:33], off offset:64
	global_load_dwordx4 v[56:59], v[32:33], off offset:512
	global_load_dwordx4 v[52:55], v[32:33], off offset:576
	s_nop 0
	global_load_dwordx4 v[32:35], v[36:37], off
	global_load_dwordx4 v[44:47], v[36:37], off offset:64
	global_load_dwordx4 v[40:43], v[36:37], off offset:512
	s_nop 0
	global_load_dwordx4 v[36:39], v[36:37], off offset:576
	s_waitcnt vmcnt(7)
	v_pk_fma_f32 v[28:29], v[28:29], v[158:159], v[48:49]
	v_lshl_add_u64 v[48:49], s[0:1], 0, v[66:67]
	v_lshl_add_u64 v[48:49], v[48:49], 0, v[172:173]
	s_waitcnt vmcnt(5)
	v_pk_fma_f32 v[18:19], v[18:19], v[164:165], v[58:59]
	v_pk_fma_f32 v[16:17], v[16:17], v[166:167], v[56:57]
	global_store_dwordx4 v[48:49], v[16:19], off offset:512
	s_waitcnt vmcnt(5)
	v_pk_fma_f32 v[10:11], v[10:11], v[168:169], v[54:55]
	v_pk_fma_f32 v[8:9], v[8:9], v[170:171], v[52:53]
	v_lshl_add_u64 v[16:17], s[0:1], 0, v[64:65]
	global_store_dwordx4 v[48:49], v[8:11], off offset:576
	v_lshl_add_u64 v[16:17], v[16:17], 0, v[172:173]
	v_pk_fma_f32 v[30:31], v[30:31], v[156:157], v[50:51]
	s_waitcnt vmcnt(5)
	v_pk_fma_f32 v[10:11], v[22:23], v[156:157], v[34:35]
	v_pk_fma_f32 v[8:9], v[20:21], v[158:159], v[32:33]
	v_pk_fma_f32 v[26:27], v[26:27], v[160:161], v[62:63]
	v_pk_fma_f32 v[24:25], v[24:25], v[162:163], v[60:61]
	global_store_dwordx4 v[16:17], v[8:11], off
	s_waitcnt vmcnt(4)
	v_pk_fma_f32 v[6:7], v[6:7], v[164:165], v[42:43]
	v_pk_fma_f32 v[4:5], v[4:5], v[166:167], v[40:41]
	v_pk_fma_f32 v[10:11], v[14:15], v[160:161], v[46:47]
	v_pk_fma_f32 v[8:9], v[12:13], v[162:163], v[44:45]
	s_waitcnt vmcnt(3)
	v_pk_fma_f32 v[2:3], v[2:3], v[168:169], v[38:39]
	v_pk_fma_f32 v[0:1], v[0:1], v[170:171], v[36:37]
	global_store_dwordx4 v[48:49], v[28:31], off
	global_store_dwordx4 v[48:49], v[24:27], off offset:64
	global_store_dwordx4 v[16:17], v[8:11], off offset:64
	global_store_dwordx4 v[16:17], v[4:7], off offset:512
	global_store_dwordx4 v[16:17], v[0:3], off offset:576
	s_waitcnt vmcnt(0)
	s_barrier
	s_and_saveexec_b64 s[46:47], s[4:5]
	s_cbranch_execz .LBB0_2375
	s_lshl_b32 s48, s44, 2
	s_ashr_i32 s49, s48, 31
	s_lshl_b64 s[48:49], s[48:49], 2
	s_add_u32 s48, s72, s48
	s_addc_u32 s49, s73, s49
	s_getreg_b32 s45, hwreg(HW_REG_XCC_ID, 0, 4)
	global_load_dwordx4 v[0:3], v131, s[48:49]
	s_and_b32 s45, s45, 15
	s_add_i32 s45, s45, 1
	s_waitcnt vmcnt(0)
	v_cmp_ne_u32_e32 vcc, s45, v2
	s_nop 1
	v_cndmask_b32_e64 v2, 0, 1, vcc
	v_cmp_ne_u32_e32 vcc, s45, v3
	v_lshlrev_b32_e32 v2, 2, v2
	s_nop 0
	v_cndmask_b32_e64 v3, 0, 1, vcc
	v_cmp_ne_u32_e32 vcc, s45, v1
	v_lshlrev_b32_e32 v3, 3, v3
	v_or_b32_e32 v2, v3, v2
	v_cndmask_b32_e64 v1, 0, 1, vcc
	v_cmp_ne_u32_e32 vcc, s45, v0
	v_lshlrev_b32_e32 v1, 1, v1
	s_nop 0
	v_cndmask_b32_e64 v0, 0, 1, vcc
	v_or_b32_e32 v0, v0, v1
	v_and_b32_e32 v0, 3, v0
	v_or_b32_e32 v0, v0, v2
	v_and_b32_e32 v0, 15, v0
	v_cmp_eq_u32_e32 vcc, 0, v0
	s_cbranch_vccnz .LBB0_2364
	buffer_wbl2 sc1
	s_waitcnt vmcnt(0)

.LBB0_2522:
	v_lshl_or_b32 v160, s60, 8, v177
	v_add_u32_e32 v144, 0x2000, v160
	v_ashrrev_i32_e32 v145, 31, v144
	s_ashr_i32 s30, s61, 3
	v_lshlrev_b64 v[148:149], 2, v[144:145]
	s_add_i32 s39, s30, 64
	v_lshl_add_u64 v[152:153], s[2:3], 0, v[148:149]
	v_lshl_add_u64 v[144:145], s[16:17], 0, v[148:149]
	v_mad_i64_i32 v[148:149], s[64:65], s39, v181, v[152:153]
	global_load_dwordx4 v[144:147], v[144:145], off
	s_add_i32 s38, s30, 0x48
	s_add_i32 s37, s30, 0x50
	s_add_i32 s36, s30, 0x58
	s_add_i32 s35, s30, 0x60
	s_add_i32 s34, s30, 0x68
	s_add_i32 s31, s30, 0x70
	s_addk_i32 s30, 0x78
	s_lshl_b32 s62, s61, 8
	global_load_dwordx4 v[148:151], v[148:149], off
	v_mad_i64_i32 v[182:183], s[64:65], s38, v181, v[152:153]
	global_load_dwordx4 v[182:185], v[182:183], off
	v_mad_i64_i32 v[186:187], s[64:65], s37, v181, v[152:153]
	global_load_dwordx4 v[186:189], v[186:187], off
	v_mad_i64_i32 v[190:191], s[64:65], s36, v181, v[152:153]
	global_load_dwordx4 v[190:193], v[190:191], off
	v_mad_i64_i32 v[200:201], s[64:65], s35, v181, v[152:153]
	global_load_dwordx4 v[200:203], v[200:201], off
	v_mad_i64_i32 v[204:205], s[64:65], s34, v181, v[152:153]
	global_load_dwordx4 v[204:207], v[204:205], off
	v_mad_i64_i32 v[208:209], s[64:65], s31, v181, v[152:153]
	global_load_dwordx4 v[208:211], v[208:209], off
	v_mad_i64_i32 v[216:217], s[64:65], s30, v181, v[152:153]
	global_load_dwordx4 v[216:219], v[216:217], off
	v_ashrrev_i32_e32 v161, 31, v160
	v_readfirstlane_b32 s63, v168
	s_waitcnt vmcnt(7)
	v_pk_add_f32 v[148:149], v[144:145], v[148:149]
	v_pk_add_f32 v[150:151], v[146:147], v[150:151]
	s_waitcnt vmcnt(6)
	v_pk_add_f32 v[148:149], v[148:149], v[182:183]
	v_pk_add_f32 v[150:151], v[150:151], v[184:185]
	s_waitcnt vmcnt(5)
	v_pk_add_f32 v[148:149], v[148:149], v[186:187]
	v_pk_add_f32 v[150:151], v[150:151], v[188:189]
	s_waitcnt vmcnt(4)
	v_pk_add_f32 v[148:149], v[148:149], v[190:191]
	v_pk_add_f32 v[150:151], v[150:151], v[192:193]
	s_waitcnt vmcnt(3)
	v_pk_add_f32 v[148:149], v[148:149], v[200:201]
	v_pk_add_f32 v[150:151], v[150:151], v[202:203]
	s_waitcnt vmcnt(2)
	v_pk_add_f32 v[148:149], v[148:149], v[204:205]
	v_pk_add_f32 v[150:151], v[150:151], v[206:207]
	s_waitcnt vmcnt(1)
	v_pk_add_f32 v[148:149], v[148:149], v[208:209]
	v_pk_add_f32 v[150:151], v[150:151], v[210:211]
	s_waitcnt vmcnt(0)
	v_pk_add_f32 v[146:147], v[150:151], v[218:219]
	v_pk_add_f32 v[148:149], v[148:149], v[216:217]
	v_pk_mul_f32 v[144:145], v[146:147], 0.5 op_sel_hi:[1, 0]
	v_pk_mul_f32 v[146:147], v[148:149], 0.5 op_sel_hi:[1, 0]
	v_add_u32_e32 v148, 0x2010, v160
	v_ashrrev_i32_e32 v149, 31, v148
	v_lshlrev_b64 v[152:153], 2, v[148:149]
	v_lshl_add_u64 v[156:157], s[2:3], 0, v[152:153]
	v_lshl_add_u64 v[148:149], s[16:17], 0, v[152:153]
	v_mad_i64_i32 v[152:153], s[64:65], s39, v181, v[156:157]
	global_load_dwordx4 v[148:151], v[148:149], off
	global_load_dwordx4 v[152:155], v[152:153], off
	v_mad_i64_i32 v[182:183], s[64:65], s38, v181, v[156:157]
	global_load_dwordx4 v[182:185], v[182:183], off
	v_mad_i64_i32 v[186:187], s[64:65], s37, v181, v[156:157]
	global_load_dwordx4 v[186:189], v[186:187], off
	v_mad_i64_i32 v[190:191], s[64:65], s36, v181, v[156:157]
	global_load_dwordx4 v[190:193], v[190:191], off
	v_mad_i64_i32 v[200:201], s[64:65], s35, v181, v[156:157]
	global_load_dwordx4 v[200:203], v[200:201], off
	v_mad_i64_i32 v[204:205], s[64:65], s34, v181, v[156:157]
	global_load_dwordx4 v[204:207], v[204:205], off
	v_mad_i64_i32 v[208:209], s[64:65], s31, v181, v[156:157]
	global_load_dwordx4 v[208:211], v[208:209], off
	v_mad_i64_i32 v[216:217], s[64:65], s30, v181, v[156:157]
	global_load_dwordx4 v[216:219], v[216:217], off
	s_waitcnt vmcnt(7)
	v_pk_add_f32 v[152:153], v[148:149], v[152:153]
	v_pk_add_f32 v[154:155], v[150:151], v[154:155]
	s_waitcnt vmcnt(6)
	v_pk_add_f32 v[152:153], v[152:153], v[182:183]
	v_pk_add_f32 v[154:155], v[154:155], v[184:185]
	s_waitcnt vmcnt(5)
	v_pk_add_f32 v[152:153], v[152:153], v[186:187]
	v_pk_add_f32 v[154:155], v[154:155], v[188:189]
	s_waitcnt vmcnt(4)
	v_pk_add_f32 v[152:153], v[152:153], v[190:191]
	v_pk_add_f32 v[154:155], v[154:155], v[192:193]
	s_waitcnt vmcnt(3)
	v_pk_add_f32 v[152:153], v[152:153], v[200:201]
	v_pk_add_f32 v[154:155], v[154:155], v[202:203]
	s_waitcnt vmcnt(2)
	v_pk_add_f32 v[152:153], v[152:153], v[204:205]
	v_pk_add_f32 v[154:155], v[154:155], v[206:207]
	s_waitcnt vmcnt(1)
	v_pk_add_f32 v[152:153], v[152:153], v[208:209]
	v_pk_add_f32 v[154:155], v[154:155], v[210:211]
	s_waitcnt vmcnt(0)
	v_pk_add_f32 v[150:151], v[154:155], v[218:219]
	v_pk_add_f32 v[152:153], v[152:153], v[216:217]
	v_pk_mul_f32 v[148:149], v[150:151], 0.5 op_sel_hi:[1, 0]
	v_pk_mul_f32 v[150:151], v[152:153], 0.5 op_sel_hi:[1, 0]
	v_add_u32_e32 v152, 0x2080, v160
	v_ashrrev_i32_e32 v153, 31, v152
	v_lshlrev_b64 v[156:157], 2, v[152:153]
	v_lshl_add_u64 v[162:163], s[2:3], 0, v[156:157]
	v_lshl_add_u64 v[152:153], s[16:17], 0, v[156:157]
	v_mad_i64_i32 v[156:157], s[64:65], s39, v181, v[162:163]
	global_load_dwordx4 v[152:155], v[152:153], off
	global_load_dwordx4 v[156:159], v[156:157], off
	v_mad_i64_i32 v[182:183], s[64:65], s38, v181, v[162:163]
	global_load_dwordx4 v[182:185], v[182:183], off
	v_mad_i64_i32 v[186:187], s[64:65], s37, v181, v[162:163]
	global_load_dwordx4 v[186:189], v[186:187], off
	v_mad_i64_i32 v[190:191], s[64:65], s36, v181, v[162:163]
	global_load_dwordx4 v[190:193], v[190:191], off
	v_mad_i64_i32 v[200:201], s[64:65], s35, v181, v[162:163]
	global_load_dwordx4 v[200:203], v[200:201], off
	v_mad_i64_i32 v[204:205], s[64:65], s34, v181, v[162:163]
	global_load_dwordx4 v[204:207], v[204:205], off
	v_mad_i64_i32 v[208:209], s[64:65], s31, v181, v[162:163]
	global_load_dwordx4 v[208:211], v[208:209], off
	v_mad_i64_i32 v[216:217], s[64:65], s30, v181, v[162:163]
	global_load_dwordx4 v[216:219], v[216:217], off
	s_waitcnt vmcnt(7)
	v_pk_add_f32 v[156:157], v[152:153], v[156:157]
	v_pk_add_f32 v[158:159], v[154:155], v[158:159]
	s_waitcnt vmcnt(6)
	v_pk_add_f32 v[156:157], v[156:157], v[182:183]
	v_pk_add_f32 v[158:159], v[158:159], v[184:185]
	s_waitcnt vmcnt(5)
	v_pk_add_f32 v[156:157], v[156:157], v[186:187]
	v_pk_add_f32 v[158:159], v[158:159], v[188:189]
	s_waitcnt vmcnt(4)
	v_pk_add_f32 v[156:157], v[156:157], v[190:191]
	v_pk_add_f32 v[158:159], v[158:159], v[192:193]
	s_waitcnt vmcnt(3)
	v_pk_add_f32 v[156:157], v[156:157], v[200:201]
	v_pk_add_f32 v[158:159], v[158:159], v[202:203]
	s_waitcnt vmcnt(2)
	v_pk_add_f32 v[156:157], v[156:157], v[204:205]
	v_pk_add_f32 v[158:159], v[158:159], v[206:207]
	s_waitcnt vmcnt(1)
	v_pk_add_f32 v[156:157], v[156:157], v[208:209]
	v_pk_add_f32 v[158:159], v[158:159], v[210:211]
	s_waitcnt vmcnt(0)
	v_pk_add_f32 v[154:155], v[158:159], v[218:219]
	v_pk_add_f32 v[156:157], v[156:157], v[216:217]
	v_pk_mul_f32 v[152:153], v[154:155], 0.5 op_sel_hi:[1, 0]
	v_pk_mul_f32 v[154:155], v[156:157], 0.5 op_sel_hi:[1, 0]
	v_add_u32_e32 v156, 0x2090, v160
	v_ashrrev_i32_e32 v157, 31, v156
	v_lshlrev_b64 v[162:163], 2, v[156:157]
	v_lshl_add_u64 v[166:167], s[2:3], 0, v[162:163]
	v_lshl_add_u64 v[156:157], s[16:17], 0, v[162:163]
	v_mad_i64_i32 v[162:163], s[64:65], s39, v181, v[166:167]
	global_load_dwordx4 v[156:159], v[156:157], off
	global_load_dwordx4 v[162:165], v[162:163], off
	v_mad_i64_i32 v[182:183], s[38:39], s38, v181, v[166:167]
	global_load_dwordx4 v[182:185], v[182:183], off
	v_mad_i64_i32 v[186:187], s[38:39], s37, v181, v[166:167]
	global_load_dwordx4 v[186:189], v[186:187], off
	v_mad_i64_i32 v[190:191], s[36:37], s36, v181, v[166:167]
	global_load_dwordx4 v[190:193], v[190:191], off
	v_mad_i64_i32 v[200:201], s[36:37], s35, v181, v[166:167]
	global_load_dwordx4 v[200:203], v[200:201], off
	v_mad_i64_i32 v[204:205], s[34:35], s34, v181, v[166:167]
	global_load_dwordx4 v[204:207], v[204:205], off
	v_mad_i64_i32 v[208:209], s[34:35], s31, v181, v[166:167]
	global_load_dwordx4 v[208:211], v[208:209], off
	v_mad_i64_i32 v[216:217], s[30:31], s30, v181, v[166:167]
	global_load_dwordx4 v[216:219], v[216:217], off
	v_lshlrev_b64 v[160:161], 2, v[160:161]
	s_waitcnt vmcnt(7)
	v_pk_add_f32 v[162:163], v[156:157], v[162:163]
	v_pk_add_f32 v[164:165], v[158:159], v[164:165]
	s_waitcnt vmcnt(6)
	v_pk_add_f32 v[162:163], v[162:163], v[182:183]
	v_pk_add_f32 v[164:165], v[164:165], v[184:185]
	s_waitcnt vmcnt(5)
	v_pk_add_f32 v[162:163], v[162:163], v[186:187]
	v_pk_add_f32 v[164:165], v[164:165], v[188:189]
	s_waitcnt vmcnt(4)
	v_pk_add_f32 v[162:163], v[162:163], v[190:191]
	v_pk_add_f32 v[164:165], v[164:165], v[192:193]
	s_waitcnt vmcnt(3)
	v_pk_add_f32 v[162:163], v[162:163], v[200:201]
	v_pk_add_f32 v[164:165], v[164:165], v[202:203]
	s_waitcnt vmcnt(2)
	v_pk_add_f32 v[162:163], v[162:163], v[204:205]
	v_pk_add_f32 v[164:165], v[164:165], v[206:207]
	s_waitcnt vmcnt(1)
	v_pk_add_f32 v[162:163], v[162:163], v[208:209]
	v_pk_add_f32 v[164:165], v[164:165], v[210:211]
	v_add_u32_e32 v166, s62, v169
	v_ashrrev_i32_e32 v167, 31, v166
	v_or_b32_e32 v198, 16, v166
	v_ashrrev_i32_e32 v199, 31, v198
	v_lshlrev_b64 v[214:215], 12, v[198:199]
	s_waitcnt vmcnt(0)
	v_pk_add_f32 v[158:159], v[164:165], v[218:219]
	v_pk_add_f32 v[162:163], v[162:163], v[216:217]
	v_pk_mul_f32 v[156:157], v[158:159], 0.5 op_sel_hi:[1, 0]
	v_pk_mul_f32 v[158:159], v[162:163], 0.5 op_sel_hi:[1, 0]
	v_lshl_add_u64 v[162:163], s[10:11], 0, v[160:161]
	v_lshlrev_b64 v[164:165], 12, v[166:167]
	v_lshl_add_u64 v[194:195], v[162:163], 0, v[164:165]
	v_mbcnt_lo_u32_b32 v180, -1, 0
	v_mbcnt_hi_u32_b32 v180, -1, v180
	v_lshrrev_b32_e32 v180, 4, v180
	v_and_b32_e32 v181, 1, v180
	v_lshlrev_b32_e32 v181, 16, v181
	v_lshrrev_b32_e32 v216, 1, v180
	v_lshl_add_u32 v181, v216, 9, v181
	v_lshlrev_b32_e32 v180, 4, v180
	v_sub_u32_e32 v180, v181, v180
	v_mov_b32_e32 v181, 0
	v_lshl_add_u64 v[180:181], v[194:195], 0, v[180:181]
	v_mov_b32_e32 v218, 0x20000
	v_mov_b32_e32 v219, 0
	v_lshl_add_u64 v[216:217], v[180:181], 0, v[218:219]
	global_load_dword v220, v[216:217], off
	v_mov_b32_e32 v218, 0x60000
	v_lshl_add_u64 v[216:217], v[216:217], 0, v[218:219]
	global_load_dword v220, v[216:217], off
	v_mov_b32_e32 v218, 0x20000
	v_lshl_add_u64 v[216:217], v[216:217], 0, v[218:219]
	global_load_dword v220, v[216:217], off
	global_load_dwordx4 v[182:185], v[194:195], off
	global_load_dwordx4 v[186:189], v[194:195], off offset:64
	global_load_dwordx4 v[190:193], v[194:195], off offset:512
	s_nop 0
	global_load_dwordx4 v[194:197], v[194:195], off offset:576
	v_lshl_add_u64 v[210:211], v[162:163], 0, v[214:215]
	global_load_dwordx4 v[198:201], v[210:211], off
	global_load_dwordx4 v[202:205], v[210:211], off offset:64
	global_load_dwordx4 v[206:209], v[210:211], off offset:512
	s_nop 0
	global_load_dwordx4 v[210:213], v[210:211], off offset:576
	s_waitcnt vmcnt(7)
	v_pk_fma_f32 v[124:125], v[124:125], v[146:147], v[182:183]
	v_lshl_add_u64 v[182:183], s[10:11], 0, v[164:165]
	v_lshl_add_u64 v[182:183], v[182:183], 0, v[160:161]
	s_waitcnt vmcnt(5)
	v_pk_fma_f32 v[110:111], v[110:111], v[152:153], v[192:193]
	v_pk_fma_f32 v[108:109], v[108:109], v[154:155], v[190:191]
	global_store_dwordx4 v[182:183], v[108:111], off offset:512
	s_waitcnt vmcnt(1)
	v_pk_fma_f32 v[98:99], v[98:99], v[156:157], v[212:213]
	v_pk_fma_f32 v[96:97], v[96:97], v[158:159], v[210:211]
	v_lshl_add_u64 v[108:109], s[10:11], 0, v[214:215]
	v_lshl_add_u64 v[108:109], v[108:109], 0, v[160:161]
	v_pk_fma_f32 v[106:107], v[106:107], v[156:157], v[196:197]
	v_pk_fma_f32 v[104:105], v[104:105], v[158:159], v[194:195]
	global_store_dwordx4 v[108:109], v[96:99], off offset:576
	v_pk_fma_f32 v[126:127], v[126:127], v[144:145], v[184:185]
	v_pk_fma_f32 v[122:123], v[122:123], v[148:149], v[188:189]
	v_or_b32_e32 v96, 32, v166
	v_pk_fma_f32 v[120:121], v[120:121], v[150:151], v[186:187]
	global_store_dwordx4 v[182:183], v[104:107], off offset:576
	v_ashrrev_i32_e32 v97, 31, v96
	global_store_dwordx4 v[182:183], v[124:127], off
	v_pk_fma_f32 v[106:107], v[118:119], v[144:145], v[200:201]
	v_pk_fma_f32 v[104:105], v[116:117], v[146:147], v[198:199]
	global_store_dwordx4 v[182:183], v[120:123], off offset:64
	global_store_dwordx4 v[108:109], v[104:107], off
	v_pk_fma_f32 v[102:103], v[102:103], v[152:153], v[208:209]
	v_pk_fma_f32 v[100:101], v[100:101], v[154:155], v[206:207]
	v_pk_fma_f32 v[106:107], v[114:115], v[148:149], v[204:205]
	v_pk_fma_f32 v[104:105], v[112:113], v[150:151], v[202:203]
	v_lshlrev_b64 v[182:183], 12, v[96:97]
	v_or_b32_e32 v112, 48, v166
	global_store_dwordx4 v[108:109], v[104:107], off offset:64
	global_store_dwordx4 v[108:109], v[100:103], off offset:512
	v_lshl_add_u64 v[108:109], v[162:163], 0, v[182:183]
	v_ashrrev_i32_e32 v113, 31, v112
	global_load_dwordx4 v[96:99], v[108:109], off
	global_load_dwordx4 v[100:103], v[108:109], off offset:64
	global_load_dwordx4 v[104:107], v[108:109], off offset:512
	s_nop 0
	global_load_dwordx4 v[108:111], v[108:109], off offset:576
	v_lshlrev_b64 v[166:167], 12, v[112:113]
	v_lshl_add_u64 v[124:125], v[162:163], 0, v[166:167]
	global_load_dwordx4 v[112:115], v[124:125], off
	global_load_dwordx4 v[116:119], v[124:125], off offset:64
	global_load_dwordx4 v[120:123], v[124:125], off offset:512
	s_nop 0
	global_load_dwordx4 v[124:127], v[124:125], off offset:576
	s_waitcnt vmcnt(7)
	v_pk_fma_f32 v[92:93], v[92:93], v[146:147], v[96:97]
	v_lshl_add_u64 v[96:97], s[10:11], 0, v[182:183]
	v_lshl_add_u64 v[96:97], v[96:97], 0, v[160:161]
	s_waitcnt vmcnt(5)
	v_pk_fma_f32 v[78:79], v[78:79], v[152:153], v[106:107]
	v_pk_fma_f32 v[76:77], v[76:77], v[154:155], v[104:105]
	global_store_dwordx4 v[96:97], v[76:79], off offset:512
	s_waitcnt vmcnt(5)
	v_pk_fma_f32 v[74:75], v[74:75], v[156:157], v[110:111]
	v_pk_fma_f32 v[72:73], v[72:73], v[158:159], v[108:109]
	v_lshl_add_u64 v[76:77], s[10:11], 0, v[166:167]
	v_pk_fma_f32 v[94:95], v[94:95], v[144:145], v[98:99]
	v_pk_fma_f32 v[90:91], v[90:91], v[148:149], v[102:103]
	v_pk_fma_f32 v[88:89], v[88:89], v[150:151], v[100:101]
	global_store_dwordx4 v[96:97], v[72:75], off offset:576
	v_lshl_add_u64 v[76:77], v[76:77], 0, v[160:161]
	global_store_dwordx4 v[96:97], v[92:95], off
	s_waitcnt vmcnt(6)
	v_pk_fma_f32 v[74:75], v[86:87], v[144:145], v[114:115]
	v_pk_fma_f32 v[72:73], v[84:85], v[146:147], v[112:113]
	global_store_dwordx4 v[96:97], v[88:91], off offset:64
	global_store_dwordx4 v[76:77], v[72:75], off
	s_waitcnt vmcnt(6)
	v_pk_fma_f32 v[70:71], v[70:71], v[152:153], v[122:123]
	v_pk_fma_f32 v[68:69], v[68:69], v[154:155], v[120:121]
	v_pk_fma_f32 v[74:75], v[82:83], v[148:149], v[118:119]
	v_pk_fma_f32 v[72:73], v[80:81], v[150:151], v[116:117]
	s_waitcnt vmcnt(5)
	v_pk_fma_f32 v[66:67], v[66:67], v[156:157], v[126:127]
	v_pk_fma_f32 v[64:65], v[64:65], v[158:159], v[124:125]
	v_lshl_add_u64 v[96:97], v[164:165], 0, s[8:9]
	global_store_dwordx4 v[76:77], v[72:75], off offset:64
	global_store_dwordx4 v[76:77], v[68:71], off offset:512
	global_store_dwordx4 v[76:77], v[64:67], off offset:576
	v_lshl_add_u64 v[76:77], v[162:163], 0, v[96:97]
	global_load_dwordx4 v[64:67], v[76:77], off
	global_load_dwordx4 v[68:71], v[76:77], off offset:64
	global_load_dwordx4 v[72:75], v[76:77], off offset:512
	s_nop 0
	global_load_dwordx4 v[76:79], v[76:77], off offset:576
	v_lshl_add_u64 v[98:99], v[164:165], 0, s[18:19]
	v_lshl_add_u64 v[92:93], v[162:163], 0, v[98:99]
	global_load_dwordx4 v[80:83], v[92:93], off
	global_load_dwordx4 v[84:87], v[92:93], off offset:64
	global_load_dwordx4 v[88:91], v[92:93], off offset:512
	s_nop 0
	global_load_dwordx4 v[92:95], v[92:93], off offset:576
	s_waitcnt vmcnt(7)
	v_pk_fma_f32 v[60:61], v[60:61], v[146:147], v[64:65]
	v_lshl_add_u64 v[64:65], s[10:11], 0, v[96:97]
	v_lshl_add_u64 v[64:65], v[64:65], 0, v[160:161]
	s_waitcnt vmcnt(5)
	v_pk_fma_f32 v[46:47], v[46:47], v[152:153], v[74:75]
	v_pk_fma_f32 v[44:45], v[44:45], v[154:155], v[72:73]
	global_store_dwordx4 v[64:65], v[44:47], off offset:512
	s_waitcnt vmcnt(5)
	v_pk_fma_f32 v[42:43], v[42:43], v[156:157], v[78:79]
	v_pk_fma_f32 v[40:41], v[40:41], v[158:159], v[76:77]
	v_lshl_add_u64 v[44:45], s[10:11], 0, v[98:99]
	v_pk_fma_f32 v[62:63], v[62:63], v[144:145], v[66:67]
	v_pk_fma_f32 v[58:59], v[58:59], v[148:149], v[70:71]
	v_pk_fma_f32 v[56:57], v[56:57], v[150:151], v[68:69]
	global_store_dwordx4 v[64:65], v[40:43], off offset:576
	v_lshl_add_u64 v[44:45], v[44:45], 0, v[160:161]
	global_store_dwordx4 v[64:65], v[60:63], off
	s_waitcnt vmcnt(6)
	v_pk_fma_f32 v[42:43], v[54:55], v[144:145], v[82:83]
	v_pk_fma_f32 v[40:41], v[52:53], v[146:147], v[80:81]
	global_store_dwordx4 v[64:65], v[56:59], off offset:64
	global_store_dwordx4 v[44:45], v[40:43], off
	s_waitcnt vmcnt(6)
	v_pk_fma_f32 v[38:39], v[38:39], v[152:153], v[90:91]
	v_pk_fma_f32 v[36:37], v[36:37], v[154:155], v[88:89]
	v_pk_fma_f32 v[42:43], v[50:51], v[148:149], v[86:87]
	v_pk_fma_f32 v[40:41], v[48:49], v[150:151], v[84:85]
	s_waitcnt vmcnt(5)
	v_pk_fma_f32 v[34:35], v[34:35], v[156:157], v[94:95]
	v_pk_fma_f32 v[32:33], v[32:33], v[158:159], v[92:93]
	v_lshl_add_u64 v[64:65], v[164:165], 0, s[20:21]
	global_store_dwordx4 v[44:45], v[40:43], off offset:64
	global_store_dwordx4 v[44:45], v[36:39], off offset:512
	global_store_dwordx4 v[44:45], v[32:35], off offset:576
	v_lshl_add_u64 v[44:45], v[162:163], 0, v[64:65]
	global_load_dwordx4 v[32:35], v[44:45], off
	global_load_dwordx4 v[36:39], v[44:45], off offset:64
	global_load_dwordx4 v[40:43], v[44:45], off offset:512
	s_nop 0
	global_load_dwordx4 v[44:47], v[44:45], off offset:576
	v_lshl_add_u64 v[66:67], v[164:165], 0, s[22:23]
	v_lshl_add_u64 v[60:61], v[162:163], 0, v[66:67]
	global_load_dwordx4 v[48:51], v[60:61], off
	global_load_dwordx4 v[52:55], v[60:61], off offset:64
	global_load_dwordx4 v[56:59], v[60:61], off offset:512
	s_nop 0
	global_load_dwordx4 v[60:63], v[60:61], off offset:576
	s_waitcnt vmcnt(7)
	v_pk_fma_f32 v[28:29], v[28:29], v[146:147], v[32:33]
	v_lshl_add_u64 v[32:33], s[10:11], 0, v[64:65]
	v_lshl_add_u64 v[32:33], v[32:33], 0, v[160:161]
	s_waitcnt vmcnt(5)
	v_pk_fma_f32 v[18:19], v[18:19], v[152:153], v[42:43]
	v_pk_fma_f32 v[16:17], v[16:17], v[154:155], v[40:41]
	global_store_dwordx4 v[32:33], v[16:19], off offset:512
	s_waitcnt vmcnt(5)
	v_pk_fma_f32 v[10:11], v[10:11], v[156:157], v[46:47]
	v_pk_fma_f32 v[8:9], v[8:9], v[158:159], v[44:45]
	v_lshl_add_u64 v[16:17], s[10:11], 0, v[66:67]
	global_store_dwordx4 v[32:33], v[8:11], off offset:576
	v_lshl_add_u64 v[16:17], v[16:17], 0, v[160:161]
	v_pk_fma_f32 v[30:31], v[30:31], v[144:145], v[34:35]
	s_waitcnt vmcnt(5)
	v_pk_fma_f32 v[10:11], v[22:23], v[144:145], v[50:51]
	v_pk_fma_f32 v[8:9], v[20:21], v[146:147], v[48:49]
	v_pk_fma_f32 v[26:27], v[26:27], v[148:149], v[38:39]
	v_pk_fma_f32 v[24:25], v[24:25], v[150:151], v[36:37]
	global_store_dwordx4 v[16:17], v[8:11], off
	s_waitcnt vmcnt(4)
	v_pk_fma_f32 v[6:7], v[6:7], v[152:153], v[58:59]
	v_pk_fma_f32 v[4:5], v[4:5], v[154:155], v[56:57]
	v_pk_fma_f32 v[10:11], v[14:15], v[148:149], v[54:55]
	v_pk_fma_f32 v[8:9], v[12:13], v[150:151], v[52:53]
	s_waitcnt vmcnt(3)
	v_pk_fma_f32 v[2:3], v[2:3], v[156:157], v[62:63]
	v_pk_fma_f32 v[0:1], v[0:1], v[158:159], v[60:61]
	global_store_dwordx4 v[32:33], v[28:31], off
	global_store_dwordx4 v[32:33], v[24:27], off offset:64
	global_store_dwordx4 v[16:17], v[8:11], off offset:64
	global_store_dwordx4 v[16:17], v[4:7], off offset:512
	global_store_dwordx4 v[16:17], v[0:3], off offset:576
	s_waitcnt vmcnt(0)
	s_barrier
	s_and_saveexec_b64 s[30:31], s[0:1]
	s_cbranch_execz .LBB0_2536
	s_lshl_b32 s34, s61, 2
	s_ashr_i32 s35, s34, 31
	s_lshl_b64 s[34:35], s[34:35], 2
	s_add_u32 s34, s49, s34
	s_addc_u32 s35, s50, s35
	s_getreg_b32 s36, hwreg(HW_REG_XCC_ID, 0, 4)
	global_load_dwordx4 v[0:3], v129, s[34:35]
	s_and_b32 s34, s36, 15
	s_add_i32 s34, s34, 1
	s_waitcnt vmcnt(0)
	v_cmp_ne_u32_e32 vcc, s34, v2
	s_nop 1
	v_cndmask_b32_e64 v2, 0, 1, vcc
	v_cmp_ne_u32_e32 vcc, s34, v3
	v_lshlrev_b32_e32 v2, 2, v2
	s_nop 0
	v_cndmask_b32_e64 v3, 0, 1, vcc
	v_cmp_ne_u32_e32 vcc, s34, v1
	v_lshlrev_b32_e32 v3, 3, v3
	v_or_b32_e32 v2, v3, v2
	v_cndmask_b32_e64 v1, 0, 1, vcc
	v_cmp_ne_u32_e32 vcc, s34, v0
	v_lshlrev_b32_e32 v1, 1, v1
	s_nop 0
	v_cndmask_b32_e64 v0, 0, 1, vcc
	v_or_b32_e32 v0, v0, v1
	v_and_b32_e32 v0, 3, v0
	v_or_b32_e32 v0, v0, v2
	v_and_b32_e32 v0, 15, v0
	v_cmp_eq_u32_e32 vcc, 0, v0
	s_cbranch_vccnz .LBB0_2525
	buffer_wbl2 sc1
	s_waitcnt vmcnt(0)
